# GEMM main loops: deleted the 32 back-to-back s_setprio 0 / s_setprio 1 no-op pairs between the two MMA blocks of a phase (doc 7.4 step b, own experiment)
# baseline (speedup 1.0000x reference)
.LBB0_150:
	ds_read_b128 v[170:173], v143
	ds_read_b128 v[174:177], v144
	ds_read_b128 v[178:181], v145
	ds_read_b128 v[182:185], v146
	ds_read_b128 v[186:189], v147
	ds_read_b128 v[198:201], v148
	ds_read_b128 v[210:213], v149
	ds_read_b128 v[214:217], v150
	s_add_u32 s22, s20, 0xfff80080
	s_addc_u32 s23, s21, -1
	s_cmp_eq_u32 s65, 28
	s_cselect_b32 s25, s13, s23
	s_cselect_b32 s24, s61, s22
	s_cselect_b32 s23, s11, s64
	s_cselect_b32 s22, s62, s63
	s_mov_b32 m0, s58
	v_lshl_add_u64 v[138:139], s[20:21], 0, v[136:137]
	ds_read_b128 v[218:221], v141
	ds_read_b128 v[222:225], v141 offset:1024
	ds_read_b128 v[226:229], v141 offset:2048
	ds_read_b128 v[230:233], v141 offset:3072
	ds_read_b128 v[244:247], v141 offset:4096
	ds_read_b128 v[248:251], v141 offset:5120
	ds_read_b128 v[202:205], v141 offset:6144
	ds_read_b128 v[240:243], v141 offset:7168
	global_load_lds_dwordx4 v[138:139], off
	v_lshl_add_u64 v[138:139], s[20:21], 0, v[134:135]
	s_mov_b32 m0, s59
	s_nop 0
	global_load_lds_dwordx4 v[138:139], off
	s_waitcnt vmcnt(8)
	s_waitcnt lgkmcnt(0)
	s_barrier
	s_setprio 1
	s_waitcnt lgkmcnt(0)
	v_mfma_f32_16x16x32_bf16 v[124:127], v[170:173], v[218:221], v[124:127]
	v_mfma_f32_16x16x32_bf16 v[120:123], v[178:181], v[218:221], v[120:123]
	v_mfma_f32_16x16x32_bf16 v[116:119], v[170:173], v[226:229], v[116:119]
	v_mfma_f32_16x16x32_bf16 v[108:111], v[178:181], v[226:229], v[108:111]
	v_mfma_f32_16x16x32_bf16 v[100:103], v[170:173], v[244:247], v[100:103]
	v_mfma_f32_16x16x32_bf16 v[92:95], v[178:181], v[244:247], v[92:95]
	v_mfma_f32_16x16x32_bf16 v[84:87], v[170:173], v[202:205], v[84:87]
	v_mfma_f32_16x16x32_bf16 v[76:79], v[178:181], v[202:205], v[76:79]
	v_mfma_f32_16x16x32_bf16 v[124:127], v[174:177], v[222:225], v[124:127]
	v_mfma_f32_16x16x32_bf16 v[120:123], v[182:185], v[222:225], v[120:123]
	v_mfma_f32_16x16x32_bf16 v[116:119], v[174:177], v[230:233], v[116:119]
	v_mfma_f32_16x16x32_bf16 v[108:111], v[182:185], v[230:233], v[108:111]
	v_mfma_f32_16x16x32_bf16 v[100:103], v[174:177], v[248:251], v[100:103]
	v_mfma_f32_16x16x32_bf16 v[92:95], v[182:185], v[248:251], v[92:95]
	v_mfma_f32_16x16x32_bf16 v[84:87], v[174:177], v[240:243], v[84:87]
	v_mfma_f32_16x16x32_bf16 v[76:79], v[182:185], v[240:243], v[76:79]
	v_mfma_f32_16x16x32_bf16 v[112:115], v[186:189], v[218:221], v[112:115]
	v_mfma_f32_16x16x32_bf16 v[104:107], v[210:213], v[218:221], v[104:107]
	v_mfma_f32_16x16x32_bf16 v[96:99], v[186:189], v[226:229], v[96:99]
	v_mfma_f32_16x16x32_bf16 v[88:91], v[210:213], v[226:229], v[88:91]
	v_mfma_f32_16x16x32_bf16 v[80:83], v[186:189], v[244:247], v[80:83]
	v_mfma_f32_16x16x32_bf16 v[72:75], v[210:213], v[244:247], v[72:75]
	v_mfma_f32_16x16x32_bf16 v[68:71], v[186:189], v[202:205], v[68:71]
	v_mfma_f32_16x16x32_bf16 v[64:67], v[210:213], v[202:205], v[64:67]
	v_mfma_f32_16x16x32_bf16 v[112:115], v[198:201], v[222:225], v[112:115]
	v_mfma_f32_16x16x32_bf16 v[104:107], v[214:217], v[222:225], v[104:107]
	v_mfma_f32_16x16x32_bf16 v[96:99], v[198:201], v[230:233], v[96:99]
	v_mfma_f32_16x16x32_bf16 v[88:91], v[214:217], v[230:233], v[88:91]
	v_mfma_f32_16x16x32_bf16 v[80:83], v[198:201], v[248:251], v[80:83]
	v_mfma_f32_16x16x32_bf16 v[72:75], v[214:217], v[248:251], v[72:75]
	v_mfma_f32_16x16x32_bf16 v[68:71], v[198:201], v[240:243], v[68:71]
	v_mfma_f32_16x16x32_bf16 v[64:67], v[214:217], v[240:243], v[64:67]
	s_setprio 0
	s_barrier
	s_mov_b32 m0, s19
	v_lshl_add_u64 v[138:139], s[22:23], 0, v[160:161]
	s_add_u32 s66, s22, 0x80000
	ds_read_b128 v[202:205], v141 offset:16384
	ds_read_b128 v[218:221], v141 offset:17408
	ds_read_b128 v[222:225], v141 offset:18432
	ds_read_b128 v[226:229], v141 offset:19456
	ds_read_b128 v[230:233], v141 offset:20480
	ds_read_b128 v[240:243], v141 offset:21504
	ds_read_b128 v[244:247], v141 offset:22528
	ds_read_b128 v[248:251], v141 offset:23552
	global_load_lds_dwordx4 v[138:139], off
	v_lshl_add_u64 v[190:191], s[22:23], 0, v[132:133]
	s_mov_b32 m0, s35
	s_addc_u32 s67, s23, 0
	global_load_lds_dwordx4 v[190:191], off
	v_lshl_add_u64 v[234:235], s[66:67], 0, v[160:161]
	s_mov_b32 m0, s36
	v_lshl_add_u64 v[206:207], s[24:25], 0, v[130:131]
	global_load_lds_dwordx4 v[234:235], off
	v_lshl_add_u64 v[234:235], s[66:67], 0, v[132:133]
	s_mov_b32 m0, s37
	s_nop 0
	global_load_lds_dwordx4 v[234:235], off
	v_lshl_add_u64 v[234:235], s[24:25], 0, v[128:129]
	s_mov_b32 m0, s34
	s_nop 0
	global_load_lds_dwordx4 v[234:235], off
	s_mov_b32 m0, s42
	s_nop 0
	global_load_lds_dwordx4 v[206:207], off
	s_waitcnt vmcnt(8)
	s_waitcnt lgkmcnt(0)
	s_barrier
	s_setprio 1
	s_waitcnt lgkmcnt(0)
	v_mfma_f32_16x16x32_bf16 v[60:63], v[170:173], v[202:205], v[60:63]
	v_mfma_f32_16x16x32_bf16 v[56:59], v[178:181], v[202:205], v[56:59]
	v_mfma_f32_16x16x32_bf16 v[52:55], v[170:173], v[222:225], v[52:55]
	v_mfma_f32_16x16x32_bf16 v[44:47], v[178:181], v[222:225], v[44:47]
	v_mfma_f32_16x16x32_bf16 v[36:39], v[170:173], v[230:233], v[36:39]
	v_mfma_f32_16x16x32_bf16 v[28:31], v[178:181], v[230:233], v[28:31]
	v_mfma_f32_16x16x32_bf16 v[20:23], v[170:173], v[244:247], v[20:23]
	v_mfma_f32_16x16x32_bf16 v[12:15], v[178:181], v[244:247], v[12:15]
	v_mfma_f32_16x16x32_bf16 v[60:63], v[174:177], v[218:221], v[60:63]
	v_mfma_f32_16x16x32_bf16 v[56:59], v[182:185], v[218:221], v[56:59]
	v_mfma_f32_16x16x32_bf16 v[52:55], v[174:177], v[226:229], v[52:55]
	v_mfma_f32_16x16x32_bf16 v[44:47], v[182:185], v[226:229], v[44:47]
	v_mfma_f32_16x16x32_bf16 v[36:39], v[174:177], v[240:243], v[36:39]
	v_mfma_f32_16x16x32_bf16 v[28:31], v[182:185], v[240:243], v[28:31]
	v_mfma_f32_16x16x32_bf16 v[20:23], v[174:177], v[248:251], v[20:23]
	v_mfma_f32_16x16x32_bf16 v[12:15], v[182:185], v[248:251], v[12:15]
	v_mfma_f32_16x16x32_bf16 v[48:51], v[186:189], v[202:205], v[48:51]
	v_mfma_f32_16x16x32_bf16 v[40:43], v[210:213], v[202:205], v[40:43]
	v_mfma_f32_16x16x32_bf16 v[32:35], v[186:189], v[222:225], v[32:35]
	v_mfma_f32_16x16x32_bf16 v[24:27], v[210:213], v[222:225], v[24:27]
	v_mfma_f32_16x16x32_bf16 v[16:19], v[186:189], v[230:233], v[16:19]
	v_mfma_f32_16x16x32_bf16 v[8:11], v[210:213], v[230:233], v[8:11]
	v_mfma_f32_16x16x32_bf16 v[4:7], v[186:189], v[244:247], v[4:7]
	v_mfma_f32_16x16x32_bf16 v[0:3], v[210:213], v[244:247], v[0:3]
	v_mfma_f32_16x16x32_bf16 v[48:51], v[198:201], v[218:221], v[48:51]
	v_mfma_f32_16x16x32_bf16 v[40:43], v[214:217], v[218:221], v[40:43]
	v_mfma_f32_16x16x32_bf16 v[32:35], v[198:201], v[226:229], v[32:35]
	v_mfma_f32_16x16x32_bf16 v[24:27], v[214:217], v[226:229], v[24:27]
	v_mfma_f32_16x16x32_bf16 v[16:19], v[198:201], v[240:243], v[16:19]
	v_mfma_f32_16x16x32_bf16 v[8:11], v[214:217], v[240:243], v[8:11]
	v_mfma_f32_16x16x32_bf16 v[4:7], v[198:201], v[248:251], v[4:7]
	v_mfma_f32_16x16x32_bf16 v[0:3], v[214:217], v[248:251], v[0:3]
	s_setprio 0
	s_barrier
	ds_read_b128 v[170:173], v151
	ds_read_b128 v[174:177], v152
	ds_read_b128 v[178:181], v153
	ds_read_b128 v[182:185], v154
	ds_read_b128 v[186:189], v155
	ds_read_b128 v[198:201], v156
	ds_read_b128 v[202:205], v157
	ds_read_b128 v[210:213], v158
	s_add_u32 s24, s24, 0x80000
	s_addc_u32 s25, s25, 0
	s_mov_b32 m0, s43
	v_lshl_add_u64 v[208:209], s[24:25], 0, v[128:129]
	ds_read_b128 v[214:217], v141 offset:32768
	ds_read_b128 v[218:221], v141 offset:33792
	ds_read_b128 v[222:225], v141 offset:34816
	ds_read_b128 v[226:229], v141 offset:35840
	ds_read_b128 v[230:233], v141 offset:36864
	ds_read_b128 v[240:243], v141 offset:37888
	ds_read_b128 v[244:247], v141 offset:38912
	ds_read_b128 v[248:251], v141 offset:39936
	global_load_lds_dwordx4 v[208:209], off
	v_lshl_add_u64 v[208:209], s[24:25], 0, v[130:131]
	s_mov_b32 m0, s44
	s_nop 0
	global_load_lds_dwordx4 v[208:209], off
	s_waitcnt vmcnt(8)
	s_waitcnt lgkmcnt(0)
	s_barrier
	s_setprio 1
	s_waitcnt lgkmcnt(0)
	v_mfma_f32_16x16x32_bf16 v[124:127], v[170:173], v[214:217], v[124:127]
	v_mfma_f32_16x16x32_bf16 v[120:123], v[178:181], v[214:217], v[120:123]
	v_mfma_f32_16x16x32_bf16 v[116:119], v[170:173], v[222:225], v[116:119]
	v_mfma_f32_16x16x32_bf16 v[108:111], v[178:181], v[222:225], v[108:111]
	v_mfma_f32_16x16x32_bf16 v[100:103], v[170:173], v[230:233], v[100:103]
	v_mfma_f32_16x16x32_bf16 v[92:95], v[178:181], v[230:233], v[92:95]
	v_mfma_f32_16x16x32_bf16 v[84:87], v[170:173], v[244:247], v[84:87]
	v_mfma_f32_16x16x32_bf16 v[76:79], v[178:181], v[244:247], v[76:79]
	v_mfma_f32_16x16x32_bf16 v[124:127], v[174:177], v[218:221], v[124:127]
	v_mfma_f32_16x16x32_bf16 v[120:123], v[182:185], v[218:221], v[120:123]
	v_mfma_f32_16x16x32_bf16 v[116:119], v[174:177], v[226:229], v[116:119]
	v_mfma_f32_16x16x32_bf16 v[108:111], v[182:185], v[226:229], v[108:111]
	v_mfma_f32_16x16x32_bf16 v[100:103], v[174:177], v[240:243], v[100:103]
	v_mfma_f32_16x16x32_bf16 v[92:95], v[182:185], v[240:243], v[92:95]
	v_mfma_f32_16x16x32_bf16 v[84:87], v[174:177], v[248:251], v[84:87]
	v_mfma_f32_16x16x32_bf16 v[76:79], v[182:185], v[248:251], v[76:79]
	v_mfma_f32_16x16x32_bf16 v[112:115], v[186:189], v[214:217], v[112:115]
	v_mfma_f32_16x16x32_bf16 v[104:107], v[202:205], v[214:217], v[104:107]
	v_mfma_f32_16x16x32_bf16 v[96:99], v[186:189], v[222:225], v[96:99]
	v_mfma_f32_16x16x32_bf16 v[88:91], v[202:205], v[222:225], v[88:91]
	v_mfma_f32_16x16x32_bf16 v[80:83], v[186:189], v[230:233], v[80:83]
	v_mfma_f32_16x16x32_bf16 v[72:75], v[202:205], v[230:233], v[72:75]
	v_mfma_f32_16x16x32_bf16 v[68:71], v[186:189], v[244:247], v[68:71]
	v_mfma_f32_16x16x32_bf16 v[64:67], v[202:205], v[244:247], v[64:67]
	v_mfma_f32_16x16x32_bf16 v[112:115], v[198:201], v[218:221], v[112:115]
	v_mfma_f32_16x16x32_bf16 v[104:107], v[210:213], v[218:221], v[104:107]
	v_mfma_f32_16x16x32_bf16 v[96:99], v[198:201], v[226:229], v[96:99]
	v_mfma_f32_16x16x32_bf16 v[88:91], v[210:213], v[226:229], v[88:91]
	v_mfma_f32_16x16x32_bf16 v[80:83], v[198:201], v[240:243], v[80:83]
	v_mfma_f32_16x16x32_bf16 v[72:75], v[210:213], v[240:243], v[72:75]
	v_mfma_f32_16x16x32_bf16 v[68:71], v[198:201], v[248:251], v[68:71]
	v_mfma_f32_16x16x32_bf16 v[64:67], v[210:213], v[248:251], v[64:67]
	s_setprio 0
	s_barrier
	s_mov_b32 m0, s45
	v_lshl_add_u64 v[138:139], v[138:139], 0, s[40:41]
	s_add_u32 s22, s22, 0x80080
	ds_read_b128 v[214:217], v141 offset:49152
	ds_read_b128 v[218:221], v141 offset:50176
	ds_read_b128 v[222:225], v141 offset:51200
	ds_read_b128 v[226:229], v141 offset:52224
	ds_read_b128 v[230:233], v141 offset:53248
	ds_read_b128 v[240:243], v141 offset:54272
	ds_read_b128 v[244:247], v141 offset:55296
	ds_read_b128 v[248:251], v141 offset:56320
	global_load_lds_dwordx4 v[138:139], off
	v_lshl_add_u64 v[138:139], v[190:191], 0, s[40:41]
	s_mov_b32 m0, s46
	s_addc_u32 s23, s23, 0
	global_load_lds_dwordx4 v[138:139], off
	v_lshl_add_u64 v[138:139], s[22:23], 0, v[160:161]
	s_mov_b32 m0, s55
	s_nop 0
	global_load_lds_dwordx4 v[138:139], off
	v_lshl_add_u64 v[138:139], s[22:23], 0, v[132:133]
	s_mov_b32 m0, s56
	s_nop 0
	global_load_lds_dwordx4 v[138:139], off
	v_lshl_add_u64 v[138:139], v[234:235], 0, s[40:41]
	s_mov_b32 m0, s47
	s_nop 0
	global_load_lds_dwordx4 v[138:139], off
	v_lshl_add_u64 v[138:139], v[206:207], 0, s[40:41]
	s_mov_b32 m0, s54
	s_nop 0
	global_load_lds_dwordx4 v[138:139], off
	s_waitcnt vmcnt(8)
	s_waitcnt lgkmcnt(0)
	s_barrier
	s_setprio 1
	s_waitcnt lgkmcnt(0)
	v_mfma_f32_16x16x32_bf16 v[60:63], v[170:173], v[214:217], v[60:63]
	v_mfma_f32_16x16x32_bf16 v[56:59], v[178:181], v[214:217], v[56:59]
	v_mfma_f32_16x16x32_bf16 v[52:55], v[170:173], v[222:225], v[52:55]
	v_mfma_f32_16x16x32_bf16 v[44:47], v[178:181], v[222:225], v[44:47]
	v_mfma_f32_16x16x32_bf16 v[36:39], v[170:173], v[230:233], v[36:39]
	v_mfma_f32_16x16x32_bf16 v[28:31], v[178:181], v[230:233], v[28:31]
	v_mfma_f32_16x16x32_bf16 v[20:23], v[170:173], v[244:247], v[20:23]
	v_mfma_f32_16x16x32_bf16 v[12:15], v[178:181], v[244:247], v[12:15]
	v_mfma_f32_16x16x32_bf16 v[60:63], v[174:177], v[218:221], v[60:63]
	v_mfma_f32_16x16x32_bf16 v[56:59], v[182:185], v[218:221], v[56:59]
	v_mfma_f32_16x16x32_bf16 v[52:55], v[174:177], v[226:229], v[52:55]
	v_mfma_f32_16x16x32_bf16 v[44:47], v[182:185], v[226:229], v[44:47]
	v_mfma_f32_16x16x32_bf16 v[36:39], v[174:177], v[240:243], v[36:39]
	v_mfma_f32_16x16x32_bf16 v[28:31], v[182:185], v[240:243], v[28:31]
	v_mfma_f32_16x16x32_bf16 v[20:23], v[174:177], v[248:251], v[20:23]
	v_mfma_f32_16x16x32_bf16 v[12:15], v[182:185], v[248:251], v[12:15]
	v_mfma_f32_16x16x32_bf16 v[48:51], v[186:189], v[214:217], v[48:51]
	v_mfma_f32_16x16x32_bf16 v[40:43], v[202:205], v[214:217], v[40:43]
	v_mfma_f32_16x16x32_bf16 v[32:35], v[186:189], v[222:225], v[32:35]
	v_mfma_f32_16x16x32_bf16 v[24:27], v[202:205], v[222:225], v[24:27]
	v_mfma_f32_16x16x32_bf16 v[16:19], v[186:189], v[230:233], v[16:19]
	v_mfma_f32_16x16x32_bf16 v[8:11], v[202:205], v[230:233], v[8:11]
	v_mfma_f32_16x16x32_bf16 v[4:7], v[186:189], v[244:247], v[4:7]
	v_mfma_f32_16x16x32_bf16 v[0:3], v[202:205], v[244:247], v[0:3]
	v_mfma_f32_16x16x32_bf16 v[48:51], v[198:201], v[218:221], v[48:51]
	v_mfma_f32_16x16x32_bf16 v[40:43], v[210:213], v[218:221], v[40:43]
	v_mfma_f32_16x16x32_bf16 v[32:35], v[198:201], v[226:229], v[32:35]
	v_mfma_f32_16x16x32_bf16 v[24:27], v[210:213], v[226:229], v[24:27]
	v_mfma_f32_16x16x32_bf16 v[16:19], v[198:201], v[240:243], v[16:19]
	v_mfma_f32_16x16x32_bf16 v[8:11], v[210:213], v[240:243], v[8:11]
	v_mfma_f32_16x16x32_bf16 v[4:7], v[198:201], v[248:251], v[4:7]
	v_mfma_f32_16x16x32_bf16 v[0:3], v[210:213], v[248:251], v[0:3]
	s_setprio 0
	s_barrier
	s_add_i32 s65, s65, 2
	s_add_u32 s63, s63, 0x100
	s_addc_u32 s64, s64, 0
	s_add_u32 s20, s20, 0x100
	s_addc_u32 s21, s21, 0
	s_cmp_gt_u32 s65, 29
	s_cbranch_scc0 .LBB0_150
	v_readlane_b32 s62, v253, 42
	s_and_b64 vcc, exec, s[8:9]
	v_readlane_b32 s63, v253, 43
	s_cbranch_vccz .LBB0_153
	s_barrier

.LBB0_176:
	v_or_b32_e32 v140, 0x10000, v146
	v_add_u32_e32 v148, 0x10400, v146
	v_add_u32_e32 v152, 0x10800, v146
	v_add_u32_e32 v156, 0x10c00, v146
	v_or_b32_e32 v170, 0x14000, v146
	v_add_u32_e32 v174, 0x14400, v146
	v_add_u32_e32 v178, 0x14800, v146
	v_add_u32_e32 v182, 0x14c00, v146
	ds_read_b128 v[140:143], v140
	ds_read_b128 v[148:151], v148
	ds_read_b128 v[152:155], v152
	ds_read_b128 v[156:159], v156
	ds_read_b128 v[170:173], v170
	ds_read_b128 v[174:177], v174
	ds_read_b128 v[178:181], v178
	ds_read_b128 v[182:185], v182
	s_add_u32 s22, s20, 0xfff80080
	s_addc_u32 s23, s21, -1
	s_cmp_eq_u32 s63, 28
	s_cselect_b32 s25, s15, s23
	s_cselect_b32 s24, s59, s22
	s_cselect_b32 s23, s13, s62
	s_cselect_b32 s22, s60, s61
	v_lshl_add_u64 v[190:191], s[20:21], 0, v[138:139]
	s_add_i32 m0, s34, 0xc000
	ds_read_b128 v[186:189], v145
	ds_read_b128 v[198:201], v145 offset:1024
	ds_read_b128 v[202:205], v145 offset:2048
	ds_read_b128 v[210:213], v145 offset:3072
	ds_read_b128 v[214:217], v145 offset:4096
	ds_read_b128 v[218:221], v145 offset:5120
	ds_read_b128 v[222:225], v145 offset:6144
	ds_read_b128 v[226:229], v145 offset:7168
	global_load_lds_dwordx4 v[190:191], off
	v_lshl_add_u64 v[190:191], s[20:21], 0, v[136:137]
	s_add_i32 m0, s34, 0xe000
	s_nop 0
	global_load_lds_dwordx4 v[190:191], off
	s_waitcnt vmcnt(8)
	s_waitcnt lgkmcnt(0)
	s_barrier
	s_setprio 1
	s_waitcnt lgkmcnt(0)
	v_mfma_f32_16x16x32_bf16 v[124:127], v[140:143], v[186:189], v[124:127]
	v_mfma_f32_16x16x32_bf16 v[120:123], v[152:155], v[186:189], v[120:123]
	v_mfma_f32_16x16x32_bf16 v[108:111], v[140:143], v[202:205], v[108:111]
	v_mfma_f32_16x16x32_bf16 v[104:107], v[152:155], v[202:205], v[104:107]
	v_mfma_f32_16x16x32_bf16 v[92:95], v[140:143], v[214:217], v[92:95]
	v_mfma_f32_16x16x32_bf16 v[88:91], v[152:155], v[214:217], v[88:91]
	v_mfma_f32_16x16x32_bf16 v[76:79], v[140:143], v[222:225], v[76:79]
	v_mfma_f32_16x16x32_bf16 v[72:75], v[152:155], v[222:225], v[72:75]
	v_mfma_f32_16x16x32_bf16 v[124:127], v[148:151], v[198:201], v[124:127]
	v_mfma_f32_16x16x32_bf16 v[120:123], v[156:159], v[198:201], v[120:123]
	v_mfma_f32_16x16x32_bf16 v[108:111], v[148:151], v[210:213], v[108:111]
	v_mfma_f32_16x16x32_bf16 v[104:107], v[156:159], v[210:213], v[104:107]
	v_mfma_f32_16x16x32_bf16 v[92:95], v[148:151], v[218:221], v[92:95]
	v_mfma_f32_16x16x32_bf16 v[88:91], v[156:159], v[218:221], v[88:91]
	v_mfma_f32_16x16x32_bf16 v[76:79], v[148:151], v[226:229], v[76:79]
	v_mfma_f32_16x16x32_bf16 v[72:75], v[156:159], v[226:229], v[72:75]
	v_mfma_f32_16x16x32_bf16 v[116:119], v[170:173], v[186:189], v[116:119]
	v_mfma_f32_16x16x32_bf16 v[112:115], v[178:181], v[186:189], v[112:115]
	v_mfma_f32_16x16x32_bf16 v[100:103], v[170:173], v[202:205], v[100:103]
	v_mfma_f32_16x16x32_bf16 v[96:99], v[178:181], v[202:205], v[96:99]
	v_mfma_f32_16x16x32_bf16 v[84:87], v[170:173], v[214:217], v[84:87]
	v_mfma_f32_16x16x32_bf16 v[80:83], v[178:181], v[214:217], v[80:83]
	v_mfma_f32_16x16x32_bf16 v[68:71], v[170:173], v[222:225], v[68:71]
	v_mfma_f32_16x16x32_bf16 v[64:67], v[178:181], v[222:225], v[64:67]
	v_mfma_f32_16x16x32_bf16 v[116:119], v[174:177], v[198:201], v[116:119]
	v_mfma_f32_16x16x32_bf16 v[112:115], v[182:185], v[198:201], v[112:115]
	v_mfma_f32_16x16x32_bf16 v[100:103], v[174:177], v[210:213], v[100:103]
	v_mfma_f32_16x16x32_bf16 v[96:99], v[182:185], v[210:213], v[96:99]
	v_mfma_f32_16x16x32_bf16 v[84:87], v[174:177], v[218:221], v[84:87]
	v_mfma_f32_16x16x32_bf16 v[80:83], v[182:185], v[218:221], v[80:83]
	v_mfma_f32_16x16x32_bf16 v[68:71], v[174:177], v[226:229], v[68:71]
	v_mfma_f32_16x16x32_bf16 v[64:67], v[182:185], v[226:229], v[64:67]
	s_setprio 0
	s_barrier
	s_mov_b32 m0, s35
	v_lshl_add_u64 v[190:191], s[22:23], 0, v[160:161]
	s_add_u32 s64, s22, 0x80000
	ds_read_b128 v[186:189], v145 offset:16384
	ds_read_b128 v[198:201], v145 offset:17408
	ds_read_b128 v[202:205], v145 offset:18432
	ds_read_b128 v[210:213], v145 offset:19456
	ds_read_b128 v[214:217], v145 offset:20480
	ds_read_b128 v[218:221], v145 offset:21504
	ds_read_b128 v[222:225], v145 offset:22528
	ds_read_b128 v[226:229], v145 offset:23552
	global_load_lds_dwordx4 v[190:191], off
	v_lshl_add_u64 v[206:207], s[22:23], 0, v[132:133]
	s_mov_b32 m0, s36
	s_addc_u32 s65, s23, 0
	global_load_lds_dwordx4 v[206:207], off
	v_lshl_add_u64 v[208:209], s[64:65], 0, v[160:161]
	s_mov_b32 m0, s37
	v_lshl_add_u64 v[230:231], s[24:25], 0, v[130:131]
	global_load_lds_dwordx4 v[208:209], off
	v_lshl_add_u64 v[208:209], s[64:65], 0, v[132:133]
	s_mov_b32 m0, s42
	s_nop 0
	global_load_lds_dwordx4 v[208:209], off
	v_lshl_add_u64 v[208:209], s[24:25], 0, v[128:129]
	s_mov_b32 m0, s34
	s_nop 0
	global_load_lds_dwordx4 v[208:209], off
	s_mov_b32 m0, s43
	s_nop 0
	global_load_lds_dwordx4 v[230:231], off
	s_waitcnt vmcnt(8)
	s_waitcnt lgkmcnt(0)
	s_barrier
	s_setprio 1
	s_waitcnt lgkmcnt(0)
	v_mfma_f32_16x16x32_bf16 v[60:63], v[140:143], v[186:189], v[60:63]
	v_mfma_f32_16x16x32_bf16 v[56:59], v[152:155], v[186:189], v[56:59]
	v_mfma_f32_16x16x32_bf16 v[44:47], v[140:143], v[202:205], v[44:47]
	v_mfma_f32_16x16x32_bf16 v[40:43], v[152:155], v[202:205], v[40:43]
	v_mfma_f32_16x16x32_bf16 v[28:31], v[140:143], v[214:217], v[28:31]
	v_mfma_f32_16x16x32_bf16 v[24:27], v[152:155], v[214:217], v[24:27]
	v_mfma_f32_16x16x32_bf16 v[12:15], v[140:143], v[222:225], v[12:15]
	v_mfma_f32_16x16x32_bf16 v[8:11], v[152:155], v[222:225], v[8:11]
	v_mfma_f32_16x16x32_bf16 v[60:63], v[148:151], v[198:201], v[60:63]
	v_mfma_f32_16x16x32_bf16 v[56:59], v[156:159], v[198:201], v[56:59]
	v_mfma_f32_16x16x32_bf16 v[44:47], v[148:151], v[210:213], v[44:47]
	v_mfma_f32_16x16x32_bf16 v[40:43], v[156:159], v[210:213], v[40:43]
	v_mfma_f32_16x16x32_bf16 v[28:31], v[148:151], v[218:221], v[28:31]
	v_mfma_f32_16x16x32_bf16 v[24:27], v[156:159], v[218:221], v[24:27]
	v_mfma_f32_16x16x32_bf16 v[12:15], v[148:151], v[226:229], v[12:15]
	v_mfma_f32_16x16x32_bf16 v[8:11], v[156:159], v[226:229], v[8:11]
	v_mfma_f32_16x16x32_bf16 v[52:55], v[170:173], v[186:189], v[52:55]
	v_mfma_f32_16x16x32_bf16 v[48:51], v[178:181], v[186:189], v[48:51]
	v_mfma_f32_16x16x32_bf16 v[36:39], v[170:173], v[202:205], v[36:39]
	v_mfma_f32_16x16x32_bf16 v[32:35], v[178:181], v[202:205], v[32:35]
	v_mfma_f32_16x16x32_bf16 v[20:23], v[170:173], v[214:217], v[20:23]
	v_mfma_f32_16x16x32_bf16 v[16:19], v[178:181], v[214:217], v[16:19]
	v_mfma_f32_16x16x32_bf16 v[4:7], v[170:173], v[222:225], v[4:7]
	v_mfma_f32_16x16x32_bf16 v[0:3], v[178:181], v[222:225], v[0:3]
	v_mfma_f32_16x16x32_bf16 v[52:55], v[174:177], v[198:201], v[52:55]
	v_mfma_f32_16x16x32_bf16 v[48:51], v[182:185], v[198:201], v[48:51]
	v_mfma_f32_16x16x32_bf16 v[36:39], v[174:177], v[210:213], v[36:39]
	v_mfma_f32_16x16x32_bf16 v[32:35], v[182:185], v[210:213], v[32:35]
	v_mfma_f32_16x16x32_bf16 v[20:23], v[174:177], v[218:221], v[20:23]
	v_mfma_f32_16x16x32_bf16 v[16:19], v[182:185], v[218:221], v[16:19]
	v_mfma_f32_16x16x32_bf16 v[4:7], v[174:177], v[226:229], v[4:7]
	v_mfma_f32_16x16x32_bf16 v[0:3], v[182:185], v[226:229], v[0:3]
	s_setprio 0
	s_barrier
	v_or_b32_e32 v140, 0x18000, v146
	v_add_u32_e32 v148, 0x18400, v146
	v_add_u32_e32 v152, 0x18800, v146
	v_add_u32_e32 v156, 0x18c00, v146
	v_or_b32_e32 v170, 0x1c000, v146
	v_add_u32_e32 v174, 0x1c400, v146
	v_add_u32_e32 v178, 0x1c800, v146
	v_add_u32_e32 v182, 0x1cc00, v146
	ds_read_b128 v[140:143], v140
	ds_read_b128 v[148:151], v148
	ds_read_b128 v[152:155], v152
	ds_read_b128 v[156:159], v156
	ds_read_b128 v[170:173], v170
	ds_read_b128 v[174:177], v174
	ds_read_b128 v[178:181], v178
	ds_read_b128 v[182:185], v182
	s_add_u32 s24, s24, 0x80000
	s_addc_u32 s25, s25, 0
	s_mov_b32 m0, s44
	v_lshl_add_u64 v[232:233], s[24:25], 0, v[128:129]
	ds_read_b128 v[186:189], v145 offset:32768
	ds_read_b128 v[198:201], v145 offset:33792
	ds_read_b128 v[202:205], v145 offset:34816
	ds_read_b128 v[210:213], v145 offset:35840
	ds_read_b128 v[214:217], v145 offset:36864
	ds_read_b128 v[218:221], v145 offset:37888
	ds_read_b128 v[222:225], v145 offset:38912
	ds_read_b128 v[226:229], v145 offset:39936
	global_load_lds_dwordx4 v[232:233], off
	v_lshl_add_u64 v[232:233], s[24:25], 0, v[130:131]
	s_mov_b32 m0, s45
	s_nop 0
	global_load_lds_dwordx4 v[232:233], off
	s_waitcnt vmcnt(8)
	s_waitcnt lgkmcnt(0)
	s_barrier
	s_setprio 1
	s_waitcnt lgkmcnt(0)
	v_mfma_f32_16x16x32_bf16 v[124:127], v[140:143], v[186:189], v[124:127]
	v_mfma_f32_16x16x32_bf16 v[120:123], v[152:155], v[186:189], v[120:123]
	v_mfma_f32_16x16x32_bf16 v[108:111], v[140:143], v[202:205], v[108:111]
	v_mfma_f32_16x16x32_bf16 v[104:107], v[152:155], v[202:205], v[104:107]
	v_mfma_f32_16x16x32_bf16 v[92:95], v[140:143], v[214:217], v[92:95]
	v_mfma_f32_16x16x32_bf16 v[88:91], v[152:155], v[214:217], v[88:91]
	v_mfma_f32_16x16x32_bf16 v[76:79], v[140:143], v[222:225], v[76:79]
	v_mfma_f32_16x16x32_bf16 v[72:75], v[152:155], v[222:225], v[72:75]
	v_mfma_f32_16x16x32_bf16 v[124:127], v[148:151], v[198:201], v[124:127]
	v_mfma_f32_16x16x32_bf16 v[120:123], v[156:159], v[198:201], v[120:123]
	v_mfma_f32_16x16x32_bf16 v[108:111], v[148:151], v[210:213], v[108:111]
	v_mfma_f32_16x16x32_bf16 v[104:107], v[156:159], v[210:213], v[104:107]
	v_mfma_f32_16x16x32_bf16 v[92:95], v[148:151], v[218:221], v[92:95]
	v_mfma_f32_16x16x32_bf16 v[88:91], v[156:159], v[218:221], v[88:91]
	v_mfma_f32_16x16x32_bf16 v[76:79], v[148:151], v[226:229], v[76:79]
	v_mfma_f32_16x16x32_bf16 v[72:75], v[156:159], v[226:229], v[72:75]
	v_mfma_f32_16x16x32_bf16 v[116:119], v[170:173], v[186:189], v[116:119]
	v_mfma_f32_16x16x32_bf16 v[112:115], v[178:181], v[186:189], v[112:115]
	v_mfma_f32_16x16x32_bf16 v[100:103], v[170:173], v[202:205], v[100:103]
	v_mfma_f32_16x16x32_bf16 v[96:99], v[178:181], v[202:205], v[96:99]
	v_mfma_f32_16x16x32_bf16 v[84:87], v[170:173], v[214:217], v[84:87]
	v_mfma_f32_16x16x32_bf16 v[80:83], v[178:181], v[214:217], v[80:83]
	v_mfma_f32_16x16x32_bf16 v[68:71], v[170:173], v[222:225], v[68:71]
	v_mfma_f32_16x16x32_bf16 v[64:67], v[178:181], v[222:225], v[64:67]
	v_mfma_f32_16x16x32_bf16 v[116:119], v[174:177], v[198:201], v[116:119]
	v_mfma_f32_16x16x32_bf16 v[112:115], v[182:185], v[198:201], v[112:115]
	v_mfma_f32_16x16x32_bf16 v[100:103], v[174:177], v[210:213], v[100:103]
	v_mfma_f32_16x16x32_bf16 v[96:99], v[182:185], v[210:213], v[96:99]
	v_mfma_f32_16x16x32_bf16 v[84:87], v[174:177], v[218:221], v[84:87]
	v_mfma_f32_16x16x32_bf16 v[80:83], v[182:185], v[218:221], v[80:83]
	v_mfma_f32_16x16x32_bf16 v[68:71], v[174:177], v[226:229], v[68:71]
	v_mfma_f32_16x16x32_bf16 v[64:67], v[182:185], v[226:229], v[64:67]
	s_setprio 0
	s_barrier
	s_mov_b32 m0, s46
	v_lshl_add_u64 v[190:191], v[190:191], 0, s[40:41]
	s_add_u32 s22, s22, 0x80080
	ds_read_b128 v[186:189], v145 offset:49152
	ds_read_b128 v[198:201], v145 offset:50176
	ds_read_b128 v[202:205], v145 offset:51200
	ds_read_b128 v[210:213], v145 offset:52224
	ds_read_b128 v[214:217], v145 offset:53248
	ds_read_b128 v[218:221], v145 offset:54272
	ds_read_b128 v[222:225], v145 offset:55296
	ds_read_b128 v[226:229], v145 offset:56320
	global_load_lds_dwordx4 v[190:191], off
	v_lshl_add_u64 v[190:191], v[206:207], 0, s[40:41]
	s_mov_b32 m0, s47
	s_addc_u32 s23, s23, 0
	global_load_lds_dwordx4 v[190:191], off
	v_lshl_add_u64 v[190:191], s[22:23], 0, v[160:161]
	s_mov_b32 m0, s56
	s_nop 0
	global_load_lds_dwordx4 v[190:191], off
	v_lshl_add_u64 v[190:191], s[22:23], 0, v[132:133]
	s_mov_b32 m0, s57
	s_nop 0
	global_load_lds_dwordx4 v[190:191], off
	v_lshl_add_u64 v[190:191], v[208:209], 0, s[40:41]
	s_mov_b32 m0, s54
	s_nop 0
	global_load_lds_dwordx4 v[190:191], off
	v_lshl_add_u64 v[190:191], v[230:231], 0, s[40:41]
	s_mov_b32 m0, s55
	s_nop 0
	global_load_lds_dwordx4 v[190:191], off
	s_waitcnt vmcnt(8)
	s_waitcnt lgkmcnt(0)
	s_barrier
	s_setprio 1
	s_waitcnt lgkmcnt(0)
	v_mfma_f32_16x16x32_bf16 v[60:63], v[140:143], v[186:189], v[60:63]
	v_mfma_f32_16x16x32_bf16 v[56:59], v[152:155], v[186:189], v[56:59]
	v_mfma_f32_16x16x32_bf16 v[44:47], v[140:143], v[202:205], v[44:47]
	v_mfma_f32_16x16x32_bf16 v[40:43], v[152:155], v[202:205], v[40:43]
	v_mfma_f32_16x16x32_bf16 v[28:31], v[140:143], v[214:217], v[28:31]
	v_mfma_f32_16x16x32_bf16 v[24:27], v[152:155], v[214:217], v[24:27]
	v_mfma_f32_16x16x32_bf16 v[12:15], v[140:143], v[222:225], v[12:15]
	v_mfma_f32_16x16x32_bf16 v[8:11], v[152:155], v[222:225], v[8:11]
	v_mfma_f32_16x16x32_bf16 v[60:63], v[148:151], v[198:201], v[60:63]
	v_mfma_f32_16x16x32_bf16 v[56:59], v[156:159], v[198:201], v[56:59]
	v_mfma_f32_16x16x32_bf16 v[44:47], v[148:151], v[210:213], v[44:47]
	v_mfma_f32_16x16x32_bf16 v[40:43], v[156:159], v[210:213], v[40:43]
	v_mfma_f32_16x16x32_bf16 v[28:31], v[148:151], v[218:221], v[28:31]
	v_mfma_f32_16x16x32_bf16 v[24:27], v[156:159], v[218:221], v[24:27]
	v_mfma_f32_16x16x32_bf16 v[12:15], v[148:151], v[226:229], v[12:15]
	v_mfma_f32_16x16x32_bf16 v[8:11], v[156:159], v[226:229], v[8:11]
	v_mfma_f32_16x16x32_bf16 v[52:55], v[170:173], v[186:189], v[52:55]
	v_mfma_f32_16x16x32_bf16 v[48:51], v[178:181], v[186:189], v[48:51]
	v_mfma_f32_16x16x32_bf16 v[36:39], v[170:173], v[202:205], v[36:39]
	v_mfma_f32_16x16x32_bf16 v[32:35], v[178:181], v[202:205], v[32:35]
	v_mfma_f32_16x16x32_bf16 v[20:23], v[170:173], v[214:217], v[20:23]
	v_mfma_f32_16x16x32_bf16 v[16:19], v[178:181], v[214:217], v[16:19]
	v_mfma_f32_16x16x32_bf16 v[4:7], v[170:173], v[222:225], v[4:7]
	v_mfma_f32_16x16x32_bf16 v[0:3], v[178:181], v[222:225], v[0:3]
	v_mfma_f32_16x16x32_bf16 v[52:55], v[174:177], v[198:201], v[52:55]
	v_mfma_f32_16x16x32_bf16 v[48:51], v[182:185], v[198:201], v[48:51]
	v_mfma_f32_16x16x32_bf16 v[36:39], v[174:177], v[210:213], v[36:39]
	v_mfma_f32_16x16x32_bf16 v[32:35], v[182:185], v[210:213], v[32:35]
	v_mfma_f32_16x16x32_bf16 v[20:23], v[174:177], v[218:221], v[20:23]
	v_mfma_f32_16x16x32_bf16 v[16:19], v[182:185], v[218:221], v[16:19]
	v_mfma_f32_16x16x32_bf16 v[4:7], v[174:177], v[226:229], v[4:7]
	v_mfma_f32_16x16x32_bf16 v[0:3], v[182:185], v[226:229], v[0:3]
	s_setprio 0
	s_barrier
	s_add_i32 s63, s63, 2
	s_add_u32 s61, s61, 0x100
	s_addc_u32 s62, s62, 0
	s_add_u32 s20, s20, 0x100
	s_addc_u32 s21, s21, 0
	s_cmp_gt_u32 s63, 29
	s_cbranch_scc0 .LBB0_176
	v_readlane_b32 s62, v253, 42
	s_and_b64 vcc, exec, s[8:9]
	s_movk_i32 s60, 0x2000
	v_readlane_b32 s63, v253, 43
	s_cbranch_vccz .LBB0_179
	s_barrier

.LBB0_318:
	v_or_b32_e32 v112, 0x10000, v189
	v_add_u32_e32 v116, 0x10400, v189
	v_add_u32_e32 v128, 0x10800, v189
	v_add_u32_e32 v140, 0x10c00, v189
	v_or_b32_e32 v144, 0x14000, v189
	v_add_u32_e32 v148, 0x14400, v189
	v_add_u32_e32 v172, 0x14800, v189
	v_add_u32_e32 v176, 0x14c00, v189
	ds_read_b128 v[112:115], v112
	ds_read_b128 v[116:119], v116
	ds_read_b128 v[128:131], v128
	ds_read_b128 v[140:143], v140
	ds_read_b128 v[144:147], v144
	ds_read_b128 v[148:151], v148
	ds_read_b128 v[172:175], v172
	ds_read_b128 v[176:179], v176
	s_add_u32 s30, s28, 0xfff80080
	s_addc_u32 s31, s29, -1
	s_cmp_eq_u32 s69, 28
	s_cselect_b32 s35, s19, s31
	s_cselect_b32 s34, s25, s30
	s_cselect_b32 s31, s17, s68
	s_cselect_b32 s30, s27, s38
	v_lshl_add_u64 v[182:183], s[28:29], 0, v[170:171]
	s_add_i32 m0, s45, 0xc000
	ds_read_b128 v[198:201], v185
	ds_read_b128 v[202:205], v185 offset:1024
	ds_read_b128 v[210:213], v185 offset:2048
	ds_read_b128 v[214:217], v185 offset:3072
	ds_read_b128 v[218:221], v185 offset:4096
	ds_read_b128 v[222:225], v185 offset:5120
	ds_read_b128 v[226:229], v185 offset:6144
	ds_read_b128 v[230:233], v185 offset:7168
	global_load_lds_dwordx4 v[182:183], off
	v_lshl_add_u64 v[182:183], s[28:29], 0, v[158:159]
	s_add_i32 m0, s45, 0xe000
	s_nop 0
	global_load_lds_dwordx4 v[182:183], off
	s_waitcnt vmcnt(8)
	s_waitcnt lgkmcnt(0)
	s_barrier
	s_setprio 1
	s_waitcnt lgkmcnt(0)
	v_mfma_f32_16x16x32_bf16 v[136:139], v[112:115], v[198:201], v[136:139]
	v_mfma_f32_16x16x32_bf16 v[132:135], v[128:131], v[198:201], v[132:135]
	v_mfma_f32_16x16x32_bf16 v[108:111], v[112:115], v[210:213], v[108:111]
	v_mfma_f32_16x16x32_bf16 v[104:107], v[128:131], v[210:213], v[104:107]
	v_mfma_f32_16x16x32_bf16 v[92:95], v[112:115], v[218:221], v[92:95]
	v_mfma_f32_16x16x32_bf16 v[88:91], v[128:131], v[218:221], v[88:91]
	v_mfma_f32_16x16x32_bf16 v[76:79], v[112:115], v[226:229], v[76:79]
	v_mfma_f32_16x16x32_bf16 v[72:75], v[128:131], v[226:229], v[72:75]
	v_mfma_f32_16x16x32_bf16 v[136:139], v[116:119], v[202:205], v[136:139]
	v_mfma_f32_16x16x32_bf16 v[132:135], v[140:143], v[202:205], v[132:135]
	v_mfma_f32_16x16x32_bf16 v[108:111], v[116:119], v[214:217], v[108:111]
	v_mfma_f32_16x16x32_bf16 v[104:107], v[140:143], v[214:217], v[104:107]
	v_mfma_f32_16x16x32_bf16 v[92:95], v[116:119], v[222:225], v[92:95]
	v_mfma_f32_16x16x32_bf16 v[88:91], v[140:143], v[222:225], v[88:91]
	v_mfma_f32_16x16x32_bf16 v[76:79], v[116:119], v[230:233], v[76:79]
	v_mfma_f32_16x16x32_bf16 v[72:75], v[140:143], v[230:233], v[72:75]
	v_mfma_f32_16x16x32_bf16 v[124:127], v[144:147], v[198:201], v[124:127]
	v_mfma_f32_16x16x32_bf16 v[120:123], v[172:175], v[198:201], v[120:123]
	v_mfma_f32_16x16x32_bf16 v[100:103], v[144:147], v[210:213], v[100:103]
	v_mfma_f32_16x16x32_bf16 v[96:99], v[172:175], v[210:213], v[96:99]
	v_mfma_f32_16x16x32_bf16 v[84:87], v[144:147], v[218:221], v[84:87]
	v_mfma_f32_16x16x32_bf16 v[80:83], v[172:175], v[218:221], v[80:83]
	v_mfma_f32_16x16x32_bf16 v[68:71], v[144:147], v[226:229], v[68:71]
	v_mfma_f32_16x16x32_bf16 v[64:67], v[172:175], v[226:229], v[64:67]
	v_mfma_f32_16x16x32_bf16 v[124:127], v[148:151], v[202:205], v[124:127]
	v_mfma_f32_16x16x32_bf16 v[120:123], v[176:179], v[202:205], v[120:123]
	v_mfma_f32_16x16x32_bf16 v[100:103], v[148:151], v[214:217], v[100:103]
	v_mfma_f32_16x16x32_bf16 v[96:99], v[176:179], v[214:217], v[96:99]
	v_mfma_f32_16x16x32_bf16 v[84:87], v[148:151], v[222:225], v[84:87]
	v_mfma_f32_16x16x32_bf16 v[80:83], v[176:179], v[222:225], v[80:83]
	v_mfma_f32_16x16x32_bf16 v[68:71], v[148:151], v[230:233], v[68:71]
	v_mfma_f32_16x16x32_bf16 v[64:67], v[176:179], v[230:233], v[64:67]
	s_setprio 0
	s_barrier
	s_mov_b32 m0, s46
	v_lshl_add_u64 v[182:183], s[30:31], 0, v[160:161]
	s_add_u32 s70, s30, 0x80000
	ds_read_b128 v[198:201], v185 offset:16384
	ds_read_b128 v[202:205], v185 offset:17408
	ds_read_b128 v[210:213], v185 offset:18432
	ds_read_b128 v[214:217], v185 offset:19456
	ds_read_b128 v[218:221], v185 offset:20480
	ds_read_b128 v[222:225], v185 offset:21504
	ds_read_b128 v[226:229], v185 offset:22528
	ds_read_b128 v[230:233], v185 offset:23552
	global_load_lds_dwordx4 v[182:183], off
	v_lshl_add_u64 v[186:187], s[30:31], 0, v[156:157]
	s_mov_b32 m0, s47
	s_addc_u32 s71, s31, 0
	global_load_lds_dwordx4 v[186:187], off
	v_lshl_add_u64 v[206:207], s[70:71], 0, v[160:161]
	s_mov_b32 m0, s54
	v_lshl_add_u64 v[208:209], s[34:35], 0, v[154:155]
	global_load_lds_dwordx4 v[206:207], off
	v_lshl_add_u64 v[206:207], s[70:71], 0, v[156:157]
	s_mov_b32 m0, s55
	s_nop 0
	global_load_lds_dwordx4 v[206:207], off
	v_lshl_add_u64 v[206:207], s[34:35], 0, v[152:153]
	s_mov_b32 m0, s45
	s_nop 0
	global_load_lds_dwordx4 v[206:207], off
	s_mov_b32 m0, s56
	s_nop 0
	global_load_lds_dwordx4 v[208:209], off
	s_waitcnt vmcnt(8)
	s_waitcnt lgkmcnt(0)
	s_barrier
	s_setprio 1
	s_waitcnt lgkmcnt(0)
	v_mfma_f32_16x16x32_bf16 v[60:63], v[112:115], v[198:201], v[60:63]
	v_mfma_f32_16x16x32_bf16 v[56:59], v[128:131], v[198:201], v[56:59]
	v_mfma_f32_16x16x32_bf16 v[44:47], v[112:115], v[210:213], v[44:47]
	v_mfma_f32_16x16x32_bf16 v[40:43], v[128:131], v[210:213], v[40:43]
	v_mfma_f32_16x16x32_bf16 v[28:31], v[112:115], v[218:221], v[28:31]
	v_mfma_f32_16x16x32_bf16 v[24:27], v[128:131], v[218:221], v[24:27]
	v_mfma_f32_16x16x32_bf16 v[12:15], v[112:115], v[226:229], v[12:15]
	v_mfma_f32_16x16x32_bf16 v[8:11], v[128:131], v[226:229], v[8:11]
	v_mfma_f32_16x16x32_bf16 v[60:63], v[116:119], v[202:205], v[60:63]
	v_mfma_f32_16x16x32_bf16 v[56:59], v[140:143], v[202:205], v[56:59]
	v_mfma_f32_16x16x32_bf16 v[44:47], v[116:119], v[214:217], v[44:47]
	v_mfma_f32_16x16x32_bf16 v[40:43], v[140:143], v[214:217], v[40:43]
	v_mfma_f32_16x16x32_bf16 v[28:31], v[116:119], v[222:225], v[28:31]
	v_mfma_f32_16x16x32_bf16 v[24:27], v[140:143], v[222:225], v[24:27]
	v_mfma_f32_16x16x32_bf16 v[12:15], v[116:119], v[230:233], v[12:15]
	v_mfma_f32_16x16x32_bf16 v[8:11], v[140:143], v[230:233], v[8:11]
	v_mfma_f32_16x16x32_bf16 v[52:55], v[144:147], v[198:201], v[52:55]
	v_mfma_f32_16x16x32_bf16 v[48:51], v[172:175], v[198:201], v[48:51]
	v_mfma_f32_16x16x32_bf16 v[36:39], v[144:147], v[210:213], v[36:39]
	v_mfma_f32_16x16x32_bf16 v[32:35], v[172:175], v[210:213], v[32:35]
	v_mfma_f32_16x16x32_bf16 v[20:23], v[144:147], v[218:221], v[20:23]
	v_mfma_f32_16x16x32_bf16 v[16:19], v[172:175], v[218:221], v[16:19]
	v_mfma_f32_16x16x32_bf16 v[4:7], v[144:147], v[226:229], v[4:7]
	v_mfma_f32_16x16x32_bf16 v[0:3], v[172:175], v[226:229], v[0:3]
	v_mfma_f32_16x16x32_bf16 v[52:55], v[148:151], v[202:205], v[52:55]
	v_mfma_f32_16x16x32_bf16 v[48:51], v[176:179], v[202:205], v[48:51]
	v_mfma_f32_16x16x32_bf16 v[36:39], v[148:151], v[214:217], v[36:39]
	v_mfma_f32_16x16x32_bf16 v[32:35], v[176:179], v[214:217], v[32:35]
	v_mfma_f32_16x16x32_bf16 v[20:23], v[148:151], v[222:225], v[20:23]
	v_mfma_f32_16x16x32_bf16 v[16:19], v[176:179], v[222:225], v[16:19]
	v_mfma_f32_16x16x32_bf16 v[4:7], v[148:151], v[230:233], v[4:7]
	v_mfma_f32_16x16x32_bf16 v[0:3], v[176:179], v[230:233], v[0:3]
	s_setprio 0
	s_barrier
	v_or_b32_e32 v112, 0x18000, v189
	v_add_u32_e32 v116, 0x18400, v189
	v_add_u32_e32 v128, 0x18800, v189
	v_add_u32_e32 v140, 0x18c00, v189
	v_or_b32_e32 v144, 0x1c000, v189
	v_add_u32_e32 v148, 0x1c400, v189
	v_add_u32_e32 v172, 0x1c800, v189
	v_add_u32_e32 v176, 0x1cc00, v189
	ds_read_b128 v[112:115], v112
	ds_read_b128 v[116:119], v116
	ds_read_b128 v[128:131], v128
	ds_read_b128 v[140:143], v140
	ds_read_b128 v[144:147], v144
	ds_read_b128 v[148:151], v148
	ds_read_b128 v[172:175], v172
	ds_read_b128 v[176:179], v176
	s_add_u32 s34, s34, 0x80000
	s_addc_u32 s35, s35, 0
	s_mov_b32 m0, s57
	v_lshl_add_u64 v[234:235], s[34:35], 0, v[152:153]
	ds_read_b128 v[198:201], v185 offset:32768
	ds_read_b128 v[202:205], v185 offset:33792
	ds_read_b128 v[210:213], v185 offset:34816
	ds_read_b128 v[214:217], v185 offset:35840
	ds_read_b128 v[218:221], v185 offset:36864
	ds_read_b128 v[222:225], v185 offset:37888
	ds_read_b128 v[226:229], v185 offset:38912
	ds_read_b128 v[230:233], v185 offset:39936
	global_load_lds_dwordx4 v[234:235], off
	v_lshl_add_u64 v[234:235], s[34:35], 0, v[154:155]
	s_mov_b32 m0, s58
	s_nop 0
	global_load_lds_dwordx4 v[234:235], off
	s_waitcnt vmcnt(8)
	s_waitcnt lgkmcnt(0)
	s_barrier
	s_setprio 1
	s_waitcnt lgkmcnt(0)
	v_mfma_f32_16x16x32_bf16 v[136:139], v[112:115], v[198:201], v[136:139]
	v_mfma_f32_16x16x32_bf16 v[132:135], v[128:131], v[198:201], v[132:135]
	v_mfma_f32_16x16x32_bf16 v[108:111], v[112:115], v[210:213], v[108:111]
	v_mfma_f32_16x16x32_bf16 v[104:107], v[128:131], v[210:213], v[104:107]
	v_mfma_f32_16x16x32_bf16 v[92:95], v[112:115], v[218:221], v[92:95]
	v_mfma_f32_16x16x32_bf16 v[88:91], v[128:131], v[218:221], v[88:91]
	v_mfma_f32_16x16x32_bf16 v[76:79], v[112:115], v[226:229], v[76:79]
	v_mfma_f32_16x16x32_bf16 v[72:75], v[128:131], v[226:229], v[72:75]
	v_mfma_f32_16x16x32_bf16 v[136:139], v[116:119], v[202:205], v[136:139]
	v_mfma_f32_16x16x32_bf16 v[132:135], v[140:143], v[202:205], v[132:135]
	v_mfma_f32_16x16x32_bf16 v[108:111], v[116:119], v[214:217], v[108:111]
	v_mfma_f32_16x16x32_bf16 v[104:107], v[140:143], v[214:217], v[104:107]
	v_mfma_f32_16x16x32_bf16 v[92:95], v[116:119], v[222:225], v[92:95]
	v_mfma_f32_16x16x32_bf16 v[88:91], v[140:143], v[222:225], v[88:91]
	v_mfma_f32_16x16x32_bf16 v[76:79], v[116:119], v[230:233], v[76:79]
	v_mfma_f32_16x16x32_bf16 v[72:75], v[140:143], v[230:233], v[72:75]
	v_mfma_f32_16x16x32_bf16 v[124:127], v[144:147], v[198:201], v[124:127]
	v_mfma_f32_16x16x32_bf16 v[120:123], v[172:175], v[198:201], v[120:123]
	v_mfma_f32_16x16x32_bf16 v[100:103], v[144:147], v[210:213], v[100:103]
	v_mfma_f32_16x16x32_bf16 v[96:99], v[172:175], v[210:213], v[96:99]
	v_mfma_f32_16x16x32_bf16 v[84:87], v[144:147], v[218:221], v[84:87]
	v_mfma_f32_16x16x32_bf16 v[80:83], v[172:175], v[218:221], v[80:83]
	v_mfma_f32_16x16x32_bf16 v[68:71], v[144:147], v[226:229], v[68:71]
	v_mfma_f32_16x16x32_bf16 v[64:67], v[172:175], v[226:229], v[64:67]
	v_mfma_f32_16x16x32_bf16 v[124:127], v[148:151], v[202:205], v[124:127]
	v_mfma_f32_16x16x32_bf16 v[120:123], v[176:179], v[202:205], v[120:123]
	v_mfma_f32_16x16x32_bf16 v[100:103], v[148:151], v[214:217], v[100:103]
	v_mfma_f32_16x16x32_bf16 v[96:99], v[176:179], v[214:217], v[96:99]
	v_mfma_f32_16x16x32_bf16 v[84:87], v[148:151], v[222:225], v[84:87]
	v_mfma_f32_16x16x32_bf16 v[80:83], v[176:179], v[222:225], v[80:83]
	v_mfma_f32_16x16x32_bf16 v[68:71], v[148:151], v[230:233], v[68:71]
	v_mfma_f32_16x16x32_bf16 v[64:67], v[176:179], v[230:233], v[64:67]
	s_setprio 0
	s_barrier
	s_mov_b32 m0, s60
	v_lshl_add_u64 v[182:183], v[182:183], 0, s[40:41]
	s_add_u32 s30, s30, 0x80080
	ds_read_b128 v[198:201], v185 offset:49152
	ds_read_b128 v[202:205], v185 offset:50176
	ds_read_b128 v[210:213], v185 offset:51200
	ds_read_b128 v[214:217], v185 offset:52224
	ds_read_b128 v[218:221], v185 offset:53248
	ds_read_b128 v[222:225], v185 offset:54272
	ds_read_b128 v[226:229], v185 offset:55296
	ds_read_b128 v[230:233], v185 offset:56320
	global_load_lds_dwordx4 v[182:183], off
	v_lshl_add_u64 v[182:183], v[186:187], 0, s[40:41]
	s_mov_b32 m0, s61
	s_addc_u32 s31, s31, 0
	global_load_lds_dwordx4 v[182:183], off
	v_lshl_add_u64 v[182:183], s[30:31], 0, v[160:161]
	s_mov_b32 m0, s64
	s_nop 0
	global_load_lds_dwordx4 v[182:183], off
	v_lshl_add_u64 v[182:183], s[30:31], 0, v[156:157]
	s_mov_b32 m0, s65
	s_nop 0
	global_load_lds_dwordx4 v[182:183], off
	v_lshl_add_u64 v[182:183], v[206:207], 0, s[40:41]
	s_mov_b32 m0, s62
	s_nop 0
	global_load_lds_dwordx4 v[182:183], off
	v_lshl_add_u64 v[182:183], v[208:209], 0, s[40:41]
	s_mov_b32 m0, s63
	s_nop 0
	global_load_lds_dwordx4 v[182:183], off
	s_waitcnt vmcnt(8)
	s_waitcnt lgkmcnt(0)
	s_barrier
	s_setprio 1
	s_waitcnt lgkmcnt(0)
	v_mfma_f32_16x16x32_bf16 v[60:63], v[112:115], v[198:201], v[60:63]
	v_mfma_f32_16x16x32_bf16 v[56:59], v[128:131], v[198:201], v[56:59]
	v_mfma_f32_16x16x32_bf16 v[44:47], v[112:115], v[210:213], v[44:47]
	v_mfma_f32_16x16x32_bf16 v[40:43], v[128:131], v[210:213], v[40:43]
	v_mfma_f32_16x16x32_bf16 v[28:31], v[112:115], v[218:221], v[28:31]
	v_mfma_f32_16x16x32_bf16 v[24:27], v[128:131], v[218:221], v[24:27]
	v_mfma_f32_16x16x32_bf16 v[12:15], v[112:115], v[226:229], v[12:15]
	v_mfma_f32_16x16x32_bf16 v[8:11], v[128:131], v[226:229], v[8:11]
	v_mfma_f32_16x16x32_bf16 v[60:63], v[116:119], v[202:205], v[60:63]
	v_mfma_f32_16x16x32_bf16 v[56:59], v[140:143], v[202:205], v[56:59]
	v_mfma_f32_16x16x32_bf16 v[44:47], v[116:119], v[214:217], v[44:47]
	v_mfma_f32_16x16x32_bf16 v[40:43], v[140:143], v[214:217], v[40:43]
	v_mfma_f32_16x16x32_bf16 v[28:31], v[116:119], v[222:225], v[28:31]
	v_mfma_f32_16x16x32_bf16 v[24:27], v[140:143], v[222:225], v[24:27]
	v_mfma_f32_16x16x32_bf16 v[12:15], v[116:119], v[230:233], v[12:15]
	v_mfma_f32_16x16x32_bf16 v[8:11], v[140:143], v[230:233], v[8:11]
	v_mfma_f32_16x16x32_bf16 v[52:55], v[144:147], v[198:201], v[52:55]
	v_mfma_f32_16x16x32_bf16 v[48:51], v[172:175], v[198:201], v[48:51]
	v_mfma_f32_16x16x32_bf16 v[36:39], v[144:147], v[210:213], v[36:39]
	v_mfma_f32_16x16x32_bf16 v[32:35], v[172:175], v[210:213], v[32:35]
	v_mfma_f32_16x16x32_bf16 v[20:23], v[144:147], v[218:221], v[20:23]
	v_mfma_f32_16x16x32_bf16 v[16:19], v[172:175], v[218:221], v[16:19]
	v_mfma_f32_16x16x32_bf16 v[4:7], v[144:147], v[226:229], v[4:7]
	v_mfma_f32_16x16x32_bf16 v[0:3], v[172:175], v[226:229], v[0:3]
	v_mfma_f32_16x16x32_bf16 v[52:55], v[148:151], v[202:205], v[52:55]
	v_mfma_f32_16x16x32_bf16 v[48:51], v[176:179], v[202:205], v[48:51]
	v_mfma_f32_16x16x32_bf16 v[36:39], v[148:151], v[214:217], v[36:39]
	v_mfma_f32_16x16x32_bf16 v[32:35], v[176:179], v[214:217], v[32:35]
	v_mfma_f32_16x16x32_bf16 v[20:23], v[148:151], v[222:225], v[20:23]
	v_mfma_f32_16x16x32_bf16 v[16:19], v[176:179], v[222:225], v[16:19]
	v_mfma_f32_16x16x32_bf16 v[4:7], v[148:151], v[230:233], v[4:7]
	v_mfma_f32_16x16x32_bf16 v[0:3], v[176:179], v[230:233], v[0:3]
	s_setprio 0
	s_barrier
	s_add_i32 s69, s69, 2
	s_add_u32 s38, s38, 0x100
	s_addc_u32 s68, s68, 0
	s_add_u32 s28, s28, 0x100
	s_addc_u32 s29, s29, 0
	s_cmp_gt_u32 s69, 29
	s_cbranch_scc0 .LBB0_318
	s_and_b64 vcc, exec, s[14:15]
	s_cbranch_vccz .LBB0_321
	s_barrier

.LBB0_478:
	v_or_b32_e32 v138, 0x10000, v144
	v_add_u32_e32 v146, 0x10400, v144
	v_add_u32_e32 v150, 0x10800, v144
	v_add_u32_e32 v154, 0x10c00, v144
	v_or_b32_e32 v158, 0x14000, v144
	ds_read_b128 v[138:141], v138
	ds_read_b128 v[146:149], v146
	ds_read_b128 v[150:153], v150
	ds_read_b128 v[154:157], v154
	v_add_u32_e32 v159, 0x14400, v144
	ds_read_b128 v[170:173], v158
	ds_read_b128 v[174:177], v159
	v_add_u32_e32 v158, 0x14800, v144
	v_add_u32_e32 v159, 0x14c00, v144
	ds_read_b128 v[178:181], v158
	ds_read_b128 v[182:185], v159
	s_add_u32 s22, s20, 0xfff80080
	s_addc_u32 s23, s21, -1
	s_cmp_eq_u32 s62, 28
	s_cselect_b32 s25, s13, s23
	s_cselect_b32 s24, s58, s22
	s_cselect_b32 s23, s11, s61
	s_cselect_b32 s22, s59, s60
	v_lshl_add_u64 v[158:159], s[20:21], 0, v[136:137]
	s_add_i32 m0, s31, 0xc000
	ds_read_b128 v[186:189], v143
	ds_read_b128 v[198:201], v143 offset:1024
	ds_read_b128 v[210:213], v143 offset:2048
	ds_read_b128 v[214:217], v143 offset:3072
	ds_read_b128 v[218:221], v143 offset:4096
	ds_read_b128 v[222:225], v143 offset:5120
	ds_read_b128 v[226:229], v143 offset:6144
	ds_read_b128 v[230:233], v143 offset:7168
	global_load_lds_dwordx4 v[158:159], off
	v_lshl_add_u64 v[158:159], s[20:21], 0, v[134:135]
	s_add_i32 m0, s31, 0xe000
	s_nop 0
	global_load_lds_dwordx4 v[158:159], off
	s_waitcnt vmcnt(8)
	s_waitcnt lgkmcnt(0)
	s_barrier
	s_setprio 1
	s_waitcnt lgkmcnt(0)
	v_mfma_f32_16x16x32_bf16 v[124:127], v[138:141], v[186:189], v[124:127]
	v_mfma_f32_16x16x32_bf16 v[120:123], v[150:153], v[186:189], v[120:123]
	v_mfma_f32_16x16x32_bf16 v[116:119], v[138:141], v[210:213], v[116:119]
	v_mfma_f32_16x16x32_bf16 v[108:111], v[150:153], v[210:213], v[108:111]
	v_mfma_f32_16x16x32_bf16 v[100:103], v[138:141], v[218:221], v[100:103]
	v_mfma_f32_16x16x32_bf16 v[92:95], v[150:153], v[218:221], v[92:95]
	v_mfma_f32_16x16x32_bf16 v[84:87], v[138:141], v[226:229], v[84:87]
	v_mfma_f32_16x16x32_bf16 v[76:79], v[150:153], v[226:229], v[76:79]
	v_mfma_f32_16x16x32_bf16 v[124:127], v[146:149], v[198:201], v[124:127]
	v_mfma_f32_16x16x32_bf16 v[120:123], v[154:157], v[198:201], v[120:123]
	v_mfma_f32_16x16x32_bf16 v[116:119], v[146:149], v[214:217], v[116:119]
	v_mfma_f32_16x16x32_bf16 v[108:111], v[154:157], v[214:217], v[108:111]
	v_mfma_f32_16x16x32_bf16 v[100:103], v[146:149], v[222:225], v[100:103]
	v_mfma_f32_16x16x32_bf16 v[92:95], v[154:157], v[222:225], v[92:95]
	v_mfma_f32_16x16x32_bf16 v[84:87], v[146:149], v[230:233], v[84:87]
	v_mfma_f32_16x16x32_bf16 v[76:79], v[154:157], v[230:233], v[76:79]
	v_mfma_f32_16x16x32_bf16 v[112:115], v[170:173], v[186:189], v[112:115]
	v_mfma_f32_16x16x32_bf16 v[104:107], v[178:181], v[186:189], v[104:107]
	v_mfma_f32_16x16x32_bf16 v[96:99], v[170:173], v[210:213], v[96:99]
	v_mfma_f32_16x16x32_bf16 v[88:91], v[178:181], v[210:213], v[88:91]
	v_mfma_f32_16x16x32_bf16 v[80:83], v[170:173], v[218:221], v[80:83]
	v_mfma_f32_16x16x32_bf16 v[72:75], v[178:181], v[218:221], v[72:75]
	v_mfma_f32_16x16x32_bf16 v[68:71], v[170:173], v[226:229], v[68:71]
	v_mfma_f32_16x16x32_bf16 v[64:67], v[178:181], v[226:229], v[64:67]
	v_mfma_f32_16x16x32_bf16 v[112:115], v[174:177], v[198:201], v[112:115]
	v_mfma_f32_16x16x32_bf16 v[104:107], v[182:185], v[198:201], v[104:107]
	v_mfma_f32_16x16x32_bf16 v[96:99], v[174:177], v[214:217], v[96:99]
	v_mfma_f32_16x16x32_bf16 v[88:91], v[182:185], v[214:217], v[88:91]
	v_mfma_f32_16x16x32_bf16 v[80:83], v[174:177], v[222:225], v[80:83]
	v_mfma_f32_16x16x32_bf16 v[72:75], v[182:185], v[222:225], v[72:75]
	v_mfma_f32_16x16x32_bf16 v[68:71], v[174:177], v[230:233], v[68:71]
	v_mfma_f32_16x16x32_bf16 v[64:67], v[182:185], v[230:233], v[64:67]
	s_setprio 0
	s_barrier
	s_mov_b32 m0, s15
	v_lshl_add_u64 v[158:159], s[22:23], 0, v[160:161]
	s_add_u32 s64, s22, 0x80000
	ds_read_b128 v[186:189], v143 offset:16384
	ds_read_b128 v[198:201], v143 offset:17408
	ds_read_b128 v[210:213], v143 offset:18432
	ds_read_b128 v[214:217], v143 offset:19456
	ds_read_b128 v[218:221], v143 offset:20480
	ds_read_b128 v[222:225], v143 offset:21504
	ds_read_b128 v[226:229], v143 offset:22528
	ds_read_b128 v[230:233], v143 offset:23552
	global_load_lds_dwordx4 v[158:159], off
	v_lshl_add_u64 v[190:191], s[22:23], 0, v[128:129]
	s_mov_b32 m0, s35
	s_addc_u32 s65, s23, 0
	global_load_lds_dwordx4 v[190:191], off
	v_lshl_add_u64 v[202:203], s[64:65], 0, v[160:161]
	s_mov_b32 m0, s36
	v_lshl_add_u64 v[204:205], s[24:25], 0, v[130:131]
	global_load_lds_dwordx4 v[202:203], off
	v_lshl_add_u64 v[202:203], s[64:65], 0, v[128:129]
	s_mov_b32 m0, s37
	s_nop 0
	global_load_lds_dwordx4 v[202:203], off
	v_lshl_add_u64 v[202:203], s[24:25], 0, v[132:133]
	s_mov_b32 m0, s31
	s_nop 0
	global_load_lds_dwordx4 v[202:203], off
	s_mov_b32 m0, s38
	s_nop 0
	global_load_lds_dwordx4 v[204:205], off
	s_waitcnt vmcnt(8)
	s_waitcnt lgkmcnt(0)
	s_barrier
	s_setprio 1
	s_waitcnt lgkmcnt(0)
	v_mfma_f32_16x16x32_bf16 v[60:63], v[138:141], v[186:189], v[60:63]
	v_mfma_f32_16x16x32_bf16 v[56:59], v[150:153], v[186:189], v[56:59]
	v_mfma_f32_16x16x32_bf16 v[52:55], v[138:141], v[210:213], v[52:55]
	v_mfma_f32_16x16x32_bf16 v[44:47], v[150:153], v[210:213], v[44:47]
	v_mfma_f32_16x16x32_bf16 v[36:39], v[138:141], v[218:221], v[36:39]
	v_mfma_f32_16x16x32_bf16 v[28:31], v[150:153], v[218:221], v[28:31]
	v_mfma_f32_16x16x32_bf16 v[20:23], v[138:141], v[226:229], v[20:23]
	v_mfma_f32_16x16x32_bf16 v[12:15], v[150:153], v[226:229], v[12:15]
	v_mfma_f32_16x16x32_bf16 v[60:63], v[146:149], v[198:201], v[60:63]
	v_mfma_f32_16x16x32_bf16 v[56:59], v[154:157], v[198:201], v[56:59]
	v_mfma_f32_16x16x32_bf16 v[52:55], v[146:149], v[214:217], v[52:55]
	v_mfma_f32_16x16x32_bf16 v[44:47], v[154:157], v[214:217], v[44:47]
	v_mfma_f32_16x16x32_bf16 v[36:39], v[146:149], v[222:225], v[36:39]
	v_mfma_f32_16x16x32_bf16 v[28:31], v[154:157], v[222:225], v[28:31]
	v_mfma_f32_16x16x32_bf16 v[20:23], v[146:149], v[230:233], v[20:23]
	v_mfma_f32_16x16x32_bf16 v[12:15], v[154:157], v[230:233], v[12:15]
	v_mfma_f32_16x16x32_bf16 v[48:51], v[170:173], v[186:189], v[48:51]
	v_mfma_f32_16x16x32_bf16 v[40:43], v[178:181], v[186:189], v[40:43]
	v_mfma_f32_16x16x32_bf16 v[32:35], v[170:173], v[210:213], v[32:35]
	v_mfma_f32_16x16x32_bf16 v[24:27], v[178:181], v[210:213], v[24:27]
	v_mfma_f32_16x16x32_bf16 v[16:19], v[170:173], v[218:221], v[16:19]
	v_mfma_f32_16x16x32_bf16 v[8:11], v[178:181], v[218:221], v[8:11]
	v_mfma_f32_16x16x32_bf16 v[4:7], v[170:173], v[226:229], v[4:7]
	v_mfma_f32_16x16x32_bf16 v[0:3], v[178:181], v[226:229], v[0:3]
	v_mfma_f32_16x16x32_bf16 v[48:51], v[174:177], v[198:201], v[48:51]
	v_mfma_f32_16x16x32_bf16 v[40:43], v[182:185], v[198:201], v[40:43]
	v_mfma_f32_16x16x32_bf16 v[32:35], v[174:177], v[214:217], v[32:35]
	v_mfma_f32_16x16x32_bf16 v[24:27], v[182:185], v[214:217], v[24:27]
	v_mfma_f32_16x16x32_bf16 v[16:19], v[174:177], v[222:225], v[16:19]
	v_mfma_f32_16x16x32_bf16 v[8:11], v[182:185], v[222:225], v[8:11]
	v_mfma_f32_16x16x32_bf16 v[4:7], v[174:177], v[230:233], v[4:7]
	v_mfma_f32_16x16x32_bf16 v[0:3], v[182:185], v[230:233], v[0:3]
	s_setprio 0
	s_barrier
	v_or_b32_e32 v138, 0x18000, v144
	v_add_u32_e32 v146, 0x18400, v144
	v_add_u32_e32 v150, 0x18800, v144
	v_add_u32_e32 v154, 0x18c00, v144
	v_or_b32_e32 v170, 0x1c000, v144
	v_add_u32_e32 v174, 0x1c400, v144
	v_add_u32_e32 v178, 0x1c800, v144
	v_add_u32_e32 v182, 0x1cc00, v144
	ds_read_b128 v[138:141], v138
	ds_read_b128 v[146:149], v146
	ds_read_b128 v[150:153], v150
	ds_read_b128 v[154:157], v154
	ds_read_b128 v[170:173], v170
	ds_read_b128 v[174:177], v174
	ds_read_b128 v[178:181], v178
	ds_read_b128 v[182:185], v182
	s_add_u32 s24, s24, 0x80000
	s_addc_u32 s25, s25, 0
	s_mov_b32 m0, s42
	v_lshl_add_u64 v[234:235], s[24:25], 0, v[132:133]
	ds_read_b128 v[186:189], v143 offset:32768
	ds_read_b128 v[198:201], v143 offset:33792
	ds_read_b128 v[210:213], v143 offset:34816
	ds_read_b128 v[214:217], v143 offset:35840
	ds_read_b128 v[218:221], v143 offset:36864
	ds_read_b128 v[222:225], v143 offset:37888
	ds_read_b128 v[226:229], v143 offset:38912
	ds_read_b128 v[230:233], v143 offset:39936
	global_load_lds_dwordx4 v[234:235], off
	v_lshl_add_u64 v[234:235], s[24:25], 0, v[130:131]
	s_mov_b32 m0, s43
	s_nop 0
	global_load_lds_dwordx4 v[234:235], off
	s_waitcnt vmcnt(8)
	s_waitcnt lgkmcnt(0)
	s_barrier
	s_setprio 1
	s_waitcnt lgkmcnt(0)
	v_mfma_f32_16x16x32_bf16 v[124:127], v[138:141], v[186:189], v[124:127]
	v_mfma_f32_16x16x32_bf16 v[120:123], v[150:153], v[186:189], v[120:123]
	v_mfma_f32_16x16x32_bf16 v[116:119], v[138:141], v[210:213], v[116:119]
	v_mfma_f32_16x16x32_bf16 v[108:111], v[150:153], v[210:213], v[108:111]
	v_mfma_f32_16x16x32_bf16 v[100:103], v[138:141], v[218:221], v[100:103]
	v_mfma_f32_16x16x32_bf16 v[92:95], v[150:153], v[218:221], v[92:95]
	v_mfma_f32_16x16x32_bf16 v[84:87], v[138:141], v[226:229], v[84:87]
	v_mfma_f32_16x16x32_bf16 v[76:79], v[150:153], v[226:229], v[76:79]
	v_mfma_f32_16x16x32_bf16 v[124:127], v[146:149], v[198:201], v[124:127]
	v_mfma_f32_16x16x32_bf16 v[120:123], v[154:157], v[198:201], v[120:123]
	v_mfma_f32_16x16x32_bf16 v[116:119], v[146:149], v[214:217], v[116:119]
	v_mfma_f32_16x16x32_bf16 v[108:111], v[154:157], v[214:217], v[108:111]
	v_mfma_f32_16x16x32_bf16 v[100:103], v[146:149], v[222:225], v[100:103]
	v_mfma_f32_16x16x32_bf16 v[92:95], v[154:157], v[222:225], v[92:95]
	v_mfma_f32_16x16x32_bf16 v[84:87], v[146:149], v[230:233], v[84:87]
	v_mfma_f32_16x16x32_bf16 v[76:79], v[154:157], v[230:233], v[76:79]
	v_mfma_f32_16x16x32_bf16 v[112:115], v[170:173], v[186:189], v[112:115]
	v_mfma_f32_16x16x32_bf16 v[104:107], v[178:181], v[186:189], v[104:107]
	v_mfma_f32_16x16x32_bf16 v[96:99], v[170:173], v[210:213], v[96:99]
	v_mfma_f32_16x16x32_bf16 v[88:91], v[178:181], v[210:213], v[88:91]
	v_mfma_f32_16x16x32_bf16 v[80:83], v[170:173], v[218:221], v[80:83]
	v_mfma_f32_16x16x32_bf16 v[72:75], v[178:181], v[218:221], v[72:75]
	v_mfma_f32_16x16x32_bf16 v[68:71], v[170:173], v[226:229], v[68:71]
	v_mfma_f32_16x16x32_bf16 v[64:67], v[178:181], v[226:229], v[64:67]
	v_mfma_f32_16x16x32_bf16 v[112:115], v[174:177], v[198:201], v[112:115]
	v_mfma_f32_16x16x32_bf16 v[104:107], v[182:185], v[198:201], v[104:107]
	v_mfma_f32_16x16x32_bf16 v[96:99], v[174:177], v[214:217], v[96:99]
	v_mfma_f32_16x16x32_bf16 v[88:91], v[182:185], v[214:217], v[88:91]
	v_mfma_f32_16x16x32_bf16 v[80:83], v[174:177], v[222:225], v[80:83]
	v_mfma_f32_16x16x32_bf16 v[72:75], v[182:185], v[222:225], v[72:75]
	v_mfma_f32_16x16x32_bf16 v[68:71], v[174:177], v[230:233], v[68:71]
	v_mfma_f32_16x16x32_bf16 v[64:67], v[182:185], v[230:233], v[64:67]
	s_setprio 0
	s_barrier
	s_mov_b32 m0, s44
	v_lshl_add_u64 v[158:159], v[158:159], 0, s[40:41]
	s_add_u32 s22, s22, 0x80080
	ds_read_b128 v[186:189], v143 offset:49152
	ds_read_b128 v[198:201], v143 offset:50176
	ds_read_b128 v[210:213], v143 offset:51200
	ds_read_b128 v[214:217], v143 offset:52224
	ds_read_b128 v[218:221], v143 offset:53248
	ds_read_b128 v[222:225], v143 offset:54272
	ds_read_b128 v[226:229], v143 offset:55296
	ds_read_b128 v[230:233], v143 offset:56320
	global_load_lds_dwordx4 v[158:159], off
	v_lshl_add_u64 v[158:159], v[190:191], 0, s[40:41]
	s_mov_b32 m0, s45
	s_addc_u32 s23, s23, 0
	global_load_lds_dwordx4 v[158:159], off
	v_lshl_add_u64 v[158:159], s[22:23], 0, v[160:161]
	s_mov_b32 m0, s54
	s_nop 0
	global_load_lds_dwordx4 v[158:159], off
	v_lshl_add_u64 v[158:159], s[22:23], 0, v[128:129]
	s_mov_b32 m0, s55
	s_nop 0
	global_load_lds_dwordx4 v[158:159], off
	v_lshl_add_u64 v[158:159], v[202:203], 0, s[40:41]
	s_mov_b32 m0, s46
	s_nop 0
	global_load_lds_dwordx4 v[158:159], off
	v_lshl_add_u64 v[158:159], v[204:205], 0, s[40:41]
	s_mov_b32 m0, s47
	s_nop 0
	global_load_lds_dwordx4 v[158:159], off
	s_waitcnt vmcnt(8)
	s_waitcnt lgkmcnt(0)
	s_barrier
	s_setprio 1
	s_waitcnt lgkmcnt(0)
	v_mfma_f32_16x16x32_bf16 v[60:63], v[138:141], v[186:189], v[60:63]
	v_mfma_f32_16x16x32_bf16 v[56:59], v[150:153], v[186:189], v[56:59]
	v_mfma_f32_16x16x32_bf16 v[52:55], v[138:141], v[210:213], v[52:55]
	v_mfma_f32_16x16x32_bf16 v[44:47], v[150:153], v[210:213], v[44:47]
	v_mfma_f32_16x16x32_bf16 v[36:39], v[138:141], v[218:221], v[36:39]
	v_mfma_f32_16x16x32_bf16 v[28:31], v[150:153], v[218:221], v[28:31]
	v_mfma_f32_16x16x32_bf16 v[20:23], v[138:141], v[226:229], v[20:23]
	v_mfma_f32_16x16x32_bf16 v[12:15], v[150:153], v[226:229], v[12:15]
	v_mfma_f32_16x16x32_bf16 v[60:63], v[146:149], v[198:201], v[60:63]
	v_mfma_f32_16x16x32_bf16 v[56:59], v[154:157], v[198:201], v[56:59]
	v_mfma_f32_16x16x32_bf16 v[52:55], v[146:149], v[214:217], v[52:55]
	v_mfma_f32_16x16x32_bf16 v[44:47], v[154:157], v[214:217], v[44:47]
	v_mfma_f32_16x16x32_bf16 v[36:39], v[146:149], v[222:225], v[36:39]
	v_mfma_f32_16x16x32_bf16 v[28:31], v[154:157], v[222:225], v[28:31]
	v_mfma_f32_16x16x32_bf16 v[20:23], v[146:149], v[230:233], v[20:23]
	v_mfma_f32_16x16x32_bf16 v[12:15], v[154:157], v[230:233], v[12:15]
	v_mfma_f32_16x16x32_bf16 v[48:51], v[170:173], v[186:189], v[48:51]
	v_mfma_f32_16x16x32_bf16 v[40:43], v[178:181], v[186:189], v[40:43]
	v_mfma_f32_16x16x32_bf16 v[32:35], v[170:173], v[210:213], v[32:35]
	v_mfma_f32_16x16x32_bf16 v[24:27], v[178:181], v[210:213], v[24:27]
	v_mfma_f32_16x16x32_bf16 v[16:19], v[170:173], v[218:221], v[16:19]
	v_mfma_f32_16x16x32_bf16 v[8:11], v[178:181], v[218:221], v[8:11]
	v_mfma_f32_16x16x32_bf16 v[4:7], v[170:173], v[226:229], v[4:7]
	v_mfma_f32_16x16x32_bf16 v[0:3], v[178:181], v[226:229], v[0:3]
	v_mfma_f32_16x16x32_bf16 v[48:51], v[174:177], v[198:201], v[48:51]
	v_mfma_f32_16x16x32_bf16 v[40:43], v[182:185], v[198:201], v[40:43]
	v_mfma_f32_16x16x32_bf16 v[32:35], v[174:177], v[214:217], v[32:35]
	v_mfma_f32_16x16x32_bf16 v[24:27], v[182:185], v[214:217], v[24:27]
	v_mfma_f32_16x16x32_bf16 v[16:19], v[174:177], v[222:225], v[16:19]
	v_mfma_f32_16x16x32_bf16 v[8:11], v[182:185], v[222:225], v[8:11]
	v_mfma_f32_16x16x32_bf16 v[4:7], v[174:177], v[230:233], v[4:7]
	v_mfma_f32_16x16x32_bf16 v[0:3], v[182:185], v[230:233], v[0:3]
	s_setprio 0
	s_barrier
	s_add_i32 s62, s62, 2
	s_add_u32 s60, s60, 0x100
	s_addc_u32 s61, s61, 0
	s_add_u32 s20, s20, 0x100
	s_addc_u32 s21, s21, 0
	s_cmp_gt_u32 s62, 29
	s_cbranch_scc0 .LBB0_478
	s_and_b64 vcc, exec, s[8:9]
	s_cbranch_vccz .LBB0_481
	s_barrier

.LBB0_828:
	v_or_b32_e32 v138, 0x10000, v142
	v_add_u32_e32 v139, 0x10400, v142
	ds_read_b128 v[144:147], v138
	ds_read_b128 v[148:151], v139
	v_add_u32_e32 v138, 0x10800, v142
	v_add_u32_e32 v139, 0x10c00, v142
	ds_read_b128 v[152:155], v138
	ds_read_b128 v[156:159], v139
	v_or_b32_e32 v138, 0x14000, v142
	v_add_u32_e32 v139, 0x14400, v142
	ds_read_b128 v[170:173], v138
	ds_read_b128 v[174:177], v139
	v_add_u32_e32 v138, 0x14800, v142
	v_add_u32_e32 v139, 0x14c00, v142
	ds_read_b128 v[178:181], v138
	ds_read_b128 v[182:185], v139
	s_add_u32 s22, s20, 0xfff80080
	s_addc_u32 s23, s21, -1
	s_cmp_eq_u32 s63, 28
	s_cselect_b32 s25, s13, s23
	s_cselect_b32 s24, s59, s22
	s_cselect_b32 s23, s11, s62
	s_cselect_b32 s22, s60, s61
	v_lshl_add_u64 v[138:139], s[20:21], 0, v[136:137]
	s_add_i32 m0, s35, 0xc000
	ds_read_b128 v[186:189], v141
	ds_read_b128 v[198:201], v141 offset:1024
	ds_read_b128 v[202:205], v141 offset:2048
	ds_read_b128 v[210:213], v141 offset:3072
	ds_read_b128 v[214:217], v141 offset:4096
	ds_read_b128 v[218:221], v141 offset:5120
	ds_read_b128 v[222:225], v141 offset:6144
	ds_read_b128 v[226:229], v141 offset:7168
	global_load_lds_dwordx4 v[138:139], off
	v_lshl_add_u64 v[138:139], s[20:21], 0, v[134:135]
	s_add_i32 m0, s35, 0xe000
	s_nop 0
	global_load_lds_dwordx4 v[138:139], off
	s_waitcnt vmcnt(8)
	s_waitcnt lgkmcnt(0)
	s_barrier
	s_setprio 1
	s_waitcnt lgkmcnt(0)
	v_mfma_f32_16x16x32_bf16 v[124:127], v[144:147], v[186:189], v[124:127]
	v_mfma_f32_16x16x32_bf16 v[120:123], v[152:155], v[186:189], v[120:123]
	v_mfma_f32_16x16x32_bf16 v[108:111], v[144:147], v[202:205], v[108:111]
	v_mfma_f32_16x16x32_bf16 v[104:107], v[152:155], v[202:205], v[104:107]
	v_mfma_f32_16x16x32_bf16 v[92:95], v[144:147], v[214:217], v[92:95]
	v_mfma_f32_16x16x32_bf16 v[88:91], v[152:155], v[214:217], v[88:91]
	v_mfma_f32_16x16x32_bf16 v[76:79], v[144:147], v[222:225], v[76:79]
	v_mfma_f32_16x16x32_bf16 v[72:75], v[152:155], v[222:225], v[72:75]
	v_mfma_f32_16x16x32_bf16 v[124:127], v[148:151], v[198:201], v[124:127]
	v_mfma_f32_16x16x32_bf16 v[120:123], v[156:159], v[198:201], v[120:123]
	v_mfma_f32_16x16x32_bf16 v[108:111], v[148:151], v[210:213], v[108:111]
	v_mfma_f32_16x16x32_bf16 v[104:107], v[156:159], v[210:213], v[104:107]
	v_mfma_f32_16x16x32_bf16 v[92:95], v[148:151], v[218:221], v[92:95]
	v_mfma_f32_16x16x32_bf16 v[88:91], v[156:159], v[218:221], v[88:91]
	v_mfma_f32_16x16x32_bf16 v[76:79], v[148:151], v[226:229], v[76:79]
	v_mfma_f32_16x16x32_bf16 v[72:75], v[156:159], v[226:229], v[72:75]
	v_mfma_f32_16x16x32_bf16 v[116:119], v[170:173], v[186:189], v[116:119]
	v_mfma_f32_16x16x32_bf16 v[112:115], v[178:181], v[186:189], v[112:115]
	v_mfma_f32_16x16x32_bf16 v[100:103], v[170:173], v[202:205], v[100:103]
	v_mfma_f32_16x16x32_bf16 v[96:99], v[178:181], v[202:205], v[96:99]
	v_mfma_f32_16x16x32_bf16 v[84:87], v[170:173], v[214:217], v[84:87]
	v_mfma_f32_16x16x32_bf16 v[80:83], v[178:181], v[214:217], v[80:83]
	v_mfma_f32_16x16x32_bf16 v[68:71], v[170:173], v[222:225], v[68:71]
	v_mfma_f32_16x16x32_bf16 v[64:67], v[178:181], v[222:225], v[64:67]
	v_mfma_f32_16x16x32_bf16 v[116:119], v[174:177], v[198:201], v[116:119]
	v_mfma_f32_16x16x32_bf16 v[112:115], v[182:185], v[198:201], v[112:115]
	v_mfma_f32_16x16x32_bf16 v[100:103], v[174:177], v[210:213], v[100:103]
	v_mfma_f32_16x16x32_bf16 v[96:99], v[182:185], v[210:213], v[96:99]
	v_mfma_f32_16x16x32_bf16 v[84:87], v[174:177], v[218:221], v[84:87]
	v_mfma_f32_16x16x32_bf16 v[80:83], v[182:185], v[218:221], v[80:83]
	v_mfma_f32_16x16x32_bf16 v[68:71], v[174:177], v[226:229], v[68:71]
	v_mfma_f32_16x16x32_bf16 v[64:67], v[182:185], v[226:229], v[64:67]
	s_setprio 0
	s_barrier
	s_mov_b32 m0, s19
	v_lshl_add_u64 v[138:139], s[22:23], 0, v[160:161]
	s_add_u32 s64, s22, 0x80000
	ds_read_b128 v[186:189], v141 offset:16384
	ds_read_b128 v[198:201], v141 offset:17408
	ds_read_b128 v[202:205], v141 offset:18432
	ds_read_b128 v[210:213], v141 offset:19456
	ds_read_b128 v[214:217], v141 offset:20480
	ds_read_b128 v[218:221], v141 offset:21504
	ds_read_b128 v[222:225], v141 offset:22528
	ds_read_b128 v[226:229], v141 offset:23552
	global_load_lds_dwordx4 v[138:139], off
	v_lshl_add_u64 v[190:191], s[22:23], 0, v[132:133]
	s_mov_b32 m0, s36
	s_addc_u32 s65, s23, 0
	global_load_lds_dwordx4 v[190:191], off
	v_lshl_add_u64 v[206:207], s[64:65], 0, v[160:161]
	s_mov_b32 m0, s37
	v_lshl_add_u64 v[208:209], s[24:25], 0, v[130:131]
	global_load_lds_dwordx4 v[206:207], off
	v_lshl_add_u64 v[206:207], s[64:65], 0, v[132:133]
	s_mov_b32 m0, s38
	s_nop 0
	global_load_lds_dwordx4 v[206:207], off
	v_lshl_add_u64 v[206:207], s[24:25], 0, v[128:129]
	s_mov_b32 m0, s35
	s_nop 0
	global_load_lds_dwordx4 v[206:207], off
	s_mov_b32 m0, s42
	s_nop 0
	global_load_lds_dwordx4 v[208:209], off
	s_waitcnt vmcnt(8)
	s_waitcnt lgkmcnt(0)
	s_barrier
	s_setprio 1
	s_waitcnt lgkmcnt(0)
	v_mfma_f32_16x16x32_bf16 v[60:63], v[144:147], v[186:189], v[60:63]
	v_mfma_f32_16x16x32_bf16 v[56:59], v[152:155], v[186:189], v[56:59]
	v_mfma_f32_16x16x32_bf16 v[44:47], v[144:147], v[202:205], v[44:47]
	v_mfma_f32_16x16x32_bf16 v[40:43], v[152:155], v[202:205], v[40:43]
	v_mfma_f32_16x16x32_bf16 v[28:31], v[144:147], v[214:217], v[28:31]
	v_mfma_f32_16x16x32_bf16 v[24:27], v[152:155], v[214:217], v[24:27]
	v_mfma_f32_16x16x32_bf16 v[12:15], v[144:147], v[222:225], v[12:15]
	v_mfma_f32_16x16x32_bf16 v[8:11], v[152:155], v[222:225], v[8:11]
	v_mfma_f32_16x16x32_bf16 v[60:63], v[148:151], v[198:201], v[60:63]
	v_mfma_f32_16x16x32_bf16 v[56:59], v[156:159], v[198:201], v[56:59]
	v_mfma_f32_16x16x32_bf16 v[44:47], v[148:151], v[210:213], v[44:47]
	v_mfma_f32_16x16x32_bf16 v[40:43], v[156:159], v[210:213], v[40:43]
	v_mfma_f32_16x16x32_bf16 v[28:31], v[148:151], v[218:221], v[28:31]
	v_mfma_f32_16x16x32_bf16 v[24:27], v[156:159], v[218:221], v[24:27]
	v_mfma_f32_16x16x32_bf16 v[12:15], v[148:151], v[226:229], v[12:15]
	v_mfma_f32_16x16x32_bf16 v[8:11], v[156:159], v[226:229], v[8:11]
	v_mfma_f32_16x16x32_bf16 v[52:55], v[170:173], v[186:189], v[52:55]
	v_mfma_f32_16x16x32_bf16 v[48:51], v[178:181], v[186:189], v[48:51]
	v_mfma_f32_16x16x32_bf16 v[36:39], v[170:173], v[202:205], v[36:39]
	v_mfma_f32_16x16x32_bf16 v[32:35], v[178:181], v[202:205], v[32:35]
	v_mfma_f32_16x16x32_bf16 v[20:23], v[170:173], v[214:217], v[20:23]
	v_mfma_f32_16x16x32_bf16 v[16:19], v[178:181], v[214:217], v[16:19]
	v_mfma_f32_16x16x32_bf16 v[4:7], v[170:173], v[222:225], v[4:7]
	v_mfma_f32_16x16x32_bf16 v[0:3], v[178:181], v[222:225], v[0:3]
	v_mfma_f32_16x16x32_bf16 v[52:55], v[174:177], v[198:201], v[52:55]
	v_mfma_f32_16x16x32_bf16 v[48:51], v[182:185], v[198:201], v[48:51]
	v_mfma_f32_16x16x32_bf16 v[36:39], v[174:177], v[210:213], v[36:39]
	v_mfma_f32_16x16x32_bf16 v[32:35], v[182:185], v[210:213], v[32:35]
	v_mfma_f32_16x16x32_bf16 v[20:23], v[174:177], v[218:221], v[20:23]
	v_mfma_f32_16x16x32_bf16 v[16:19], v[182:185], v[218:221], v[16:19]
	v_mfma_f32_16x16x32_bf16 v[4:7], v[174:177], v[226:229], v[4:7]
	v_mfma_f32_16x16x32_bf16 v[0:3], v[182:185], v[226:229], v[0:3]
	s_setprio 0
	s_barrier
	v_or_b32_e32 v144, 0x18000, v142
	v_add_u32_e32 v148, 0x18400, v142
	v_add_u32_e32 v152, 0x18800, v142
	v_add_u32_e32 v156, 0x18c00, v142
	v_or_b32_e32 v170, 0x1c000, v142
	v_add_u32_e32 v174, 0x1c400, v142
	v_add_u32_e32 v178, 0x1c800, v142
	v_add_u32_e32 v182, 0x1cc00, v142
	ds_read_b128 v[144:147], v144
	ds_read_b128 v[148:151], v148
	ds_read_b128 v[152:155], v152
	ds_read_b128 v[156:159], v156
	ds_read_b128 v[170:173], v170
	ds_read_b128 v[174:177], v174
	ds_read_b128 v[178:181], v178
	ds_read_b128 v[182:185], v182
	s_add_u32 s24, s24, 0x80000
	s_addc_u32 s25, s25, 0
	s_mov_b32 m0, s43
	v_lshl_add_u64 v[230:231], s[24:25], 0, v[128:129]
	ds_read_b128 v[186:189], v141 offset:32768
	ds_read_b128 v[198:201], v141 offset:33792
	ds_read_b128 v[202:205], v141 offset:34816
	ds_read_b128 v[210:213], v141 offset:35840
	ds_read_b128 v[214:217], v141 offset:36864
	ds_read_b128 v[218:221], v141 offset:37888
	ds_read_b128 v[222:225], v141 offset:38912
	ds_read_b128 v[226:229], v141 offset:39936
	global_load_lds_dwordx4 v[230:231], off
	v_lshl_add_u64 v[230:231], s[24:25], 0, v[130:131]
	s_mov_b32 m0, s44
	s_nop 0
	global_load_lds_dwordx4 v[230:231], off
	s_waitcnt vmcnt(8)
	s_waitcnt lgkmcnt(0)
	s_barrier
	s_setprio 1
	s_waitcnt lgkmcnt(0)
	v_mfma_f32_16x16x32_bf16 v[124:127], v[144:147], v[186:189], v[124:127]
	v_mfma_f32_16x16x32_bf16 v[120:123], v[152:155], v[186:189], v[120:123]
	v_mfma_f32_16x16x32_bf16 v[108:111], v[144:147], v[202:205], v[108:111]
	v_mfma_f32_16x16x32_bf16 v[104:107], v[152:155], v[202:205], v[104:107]
	v_mfma_f32_16x16x32_bf16 v[92:95], v[144:147], v[214:217], v[92:95]
	v_mfma_f32_16x16x32_bf16 v[88:91], v[152:155], v[214:217], v[88:91]
	v_mfma_f32_16x16x32_bf16 v[76:79], v[144:147], v[222:225], v[76:79]
	v_mfma_f32_16x16x32_bf16 v[72:75], v[152:155], v[222:225], v[72:75]
	v_mfma_f32_16x16x32_bf16 v[124:127], v[148:151], v[198:201], v[124:127]
	v_mfma_f32_16x16x32_bf16 v[120:123], v[156:159], v[198:201], v[120:123]
	v_mfma_f32_16x16x32_bf16 v[108:111], v[148:151], v[210:213], v[108:111]
	v_mfma_f32_16x16x32_bf16 v[104:107], v[156:159], v[210:213], v[104:107]
	v_mfma_f32_16x16x32_bf16 v[92:95], v[148:151], v[218:221], v[92:95]
	v_mfma_f32_16x16x32_bf16 v[88:91], v[156:159], v[218:221], v[88:91]
	v_mfma_f32_16x16x32_bf16 v[76:79], v[148:151], v[226:229], v[76:79]
	v_mfma_f32_16x16x32_bf16 v[72:75], v[156:159], v[226:229], v[72:75]
	v_mfma_f32_16x16x32_bf16 v[116:119], v[170:173], v[186:189], v[116:119]
	v_mfma_f32_16x16x32_bf16 v[112:115], v[178:181], v[186:189], v[112:115]
	v_mfma_f32_16x16x32_bf16 v[100:103], v[170:173], v[202:205], v[100:103]
	v_mfma_f32_16x16x32_bf16 v[96:99], v[178:181], v[202:205], v[96:99]
	v_mfma_f32_16x16x32_bf16 v[84:87], v[170:173], v[214:217], v[84:87]
	v_mfma_f32_16x16x32_bf16 v[80:83], v[178:181], v[214:217], v[80:83]
	v_mfma_f32_16x16x32_bf16 v[68:71], v[170:173], v[222:225], v[68:71]
	v_mfma_f32_16x16x32_bf16 v[64:67], v[178:181], v[222:225], v[64:67]
	v_mfma_f32_16x16x32_bf16 v[116:119], v[174:177], v[198:201], v[116:119]
	v_mfma_f32_16x16x32_bf16 v[112:115], v[182:185], v[198:201], v[112:115]
	v_mfma_f32_16x16x32_bf16 v[100:103], v[174:177], v[210:213], v[100:103]
	v_mfma_f32_16x16x32_bf16 v[96:99], v[182:185], v[210:213], v[96:99]
	v_mfma_f32_16x16x32_bf16 v[84:87], v[174:177], v[218:221], v[84:87]
	v_mfma_f32_16x16x32_bf16 v[80:83], v[182:185], v[218:221], v[80:83]
	v_mfma_f32_16x16x32_bf16 v[68:71], v[174:177], v[226:229], v[68:71]
	v_mfma_f32_16x16x32_bf16 v[64:67], v[182:185], v[226:229], v[64:67]
	s_setprio 0
	s_barrier
	s_mov_b32 m0, s45
	v_lshl_add_u64 v[138:139], v[138:139], 0, s[40:41]
	s_add_u32 s22, s22, 0x80080
	ds_read_b128 v[186:189], v141 offset:49152
	ds_read_b128 v[198:201], v141 offset:50176
	ds_read_b128 v[202:205], v141 offset:51200
	ds_read_b128 v[210:213], v141 offset:52224
	ds_read_b128 v[214:217], v141 offset:53248
	ds_read_b128 v[218:221], v141 offset:54272
	ds_read_b128 v[222:225], v141 offset:55296
	ds_read_b128 v[226:229], v141 offset:56320
	global_load_lds_dwordx4 v[138:139], off
	v_lshl_add_u64 v[138:139], v[190:191], 0, s[40:41]
	s_mov_b32 m0, s46
	s_addc_u32 s23, s23, 0
	global_load_lds_dwordx4 v[138:139], off
	v_lshl_add_u64 v[138:139], s[22:23], 0, v[160:161]
	s_mov_b32 m0, s55
	s_nop 0
	global_load_lds_dwordx4 v[138:139], off
	v_lshl_add_u64 v[138:139], s[22:23], 0, v[132:133]
	s_mov_b32 m0, s56
	s_nop 0
	global_load_lds_dwordx4 v[138:139], off
	v_lshl_add_u64 v[138:139], v[206:207], 0, s[40:41]
	s_mov_b32 m0, s47
	s_nop 0
	global_load_lds_dwordx4 v[138:139], off
	v_lshl_add_u64 v[138:139], v[208:209], 0, s[40:41]
	s_mov_b32 m0, s54
	s_nop 0
	global_load_lds_dwordx4 v[138:139], off
	s_waitcnt vmcnt(8)
	s_waitcnt lgkmcnt(0)
	s_barrier
	s_setprio 1
	s_waitcnt lgkmcnt(0)
	v_mfma_f32_16x16x32_bf16 v[60:63], v[144:147], v[186:189], v[60:63]
	v_mfma_f32_16x16x32_bf16 v[56:59], v[152:155], v[186:189], v[56:59]
	v_mfma_f32_16x16x32_bf16 v[44:47], v[144:147], v[202:205], v[44:47]
	v_mfma_f32_16x16x32_bf16 v[40:43], v[152:155], v[202:205], v[40:43]
	v_mfma_f32_16x16x32_bf16 v[28:31], v[144:147], v[214:217], v[28:31]
	v_mfma_f32_16x16x32_bf16 v[24:27], v[152:155], v[214:217], v[24:27]
	v_mfma_f32_16x16x32_bf16 v[12:15], v[144:147], v[222:225], v[12:15]
	v_mfma_f32_16x16x32_bf16 v[8:11], v[152:155], v[222:225], v[8:11]
	v_mfma_f32_16x16x32_bf16 v[60:63], v[148:151], v[198:201], v[60:63]
	v_mfma_f32_16x16x32_bf16 v[56:59], v[156:159], v[198:201], v[56:59]
	v_mfma_f32_16x16x32_bf16 v[44:47], v[148:151], v[210:213], v[44:47]
	v_mfma_f32_16x16x32_bf16 v[40:43], v[156:159], v[210:213], v[40:43]
	v_mfma_f32_16x16x32_bf16 v[28:31], v[148:151], v[218:221], v[28:31]
	v_mfma_f32_16x16x32_bf16 v[24:27], v[156:159], v[218:221], v[24:27]
	v_mfma_f32_16x16x32_bf16 v[12:15], v[148:151], v[226:229], v[12:15]
	v_mfma_f32_16x16x32_bf16 v[8:11], v[156:159], v[226:229], v[8:11]
	v_mfma_f32_16x16x32_bf16 v[52:55], v[170:173], v[186:189], v[52:55]
	v_mfma_f32_16x16x32_bf16 v[48:51], v[178:181], v[186:189], v[48:51]
	v_mfma_f32_16x16x32_bf16 v[36:39], v[170:173], v[202:205], v[36:39]
	v_mfma_f32_16x16x32_bf16 v[32:35], v[178:181], v[202:205], v[32:35]
	v_mfma_f32_16x16x32_bf16 v[20:23], v[170:173], v[214:217], v[20:23]
	v_mfma_f32_16x16x32_bf16 v[16:19], v[178:181], v[214:217], v[16:19]
	v_mfma_f32_16x16x32_bf16 v[4:7], v[170:173], v[222:225], v[4:7]
	v_mfma_f32_16x16x32_bf16 v[0:3], v[178:181], v[222:225], v[0:3]
	v_mfma_f32_16x16x32_bf16 v[52:55], v[174:177], v[198:201], v[52:55]
	v_mfma_f32_16x16x32_bf16 v[48:51], v[182:185], v[198:201], v[48:51]
	v_mfma_f32_16x16x32_bf16 v[36:39], v[174:177], v[210:213], v[36:39]
	v_mfma_f32_16x16x32_bf16 v[32:35], v[182:185], v[210:213], v[32:35]
	v_mfma_f32_16x16x32_bf16 v[20:23], v[174:177], v[218:221], v[20:23]
	v_mfma_f32_16x16x32_bf16 v[16:19], v[182:185], v[218:221], v[16:19]
	v_mfma_f32_16x16x32_bf16 v[4:7], v[174:177], v[226:229], v[4:7]
	v_mfma_f32_16x16x32_bf16 v[0:3], v[182:185], v[226:229], v[0:3]
	s_setprio 0
	s_barrier
	s_add_i32 s63, s63, 2
	s_add_u32 s61, s61, 0x100
	s_addc_u32 s62, s62, 0
	s_add_u32 s20, s20, 0x100
	s_addc_u32 s21, s21, 0
	s_cmp_gt_u32 s63, 29
	s_cbranch_scc0 .LBB0_828
	v_readlane_b32 s62, v253, 42
	s_and_b64 vcc, exec, s[8:9]
	s_movk_i32 s60, 0x2000
	v_readlane_b32 s63, v253, 43
	s_cbranch_vccz .LBB0_831
	s_barrier

.LBB0_916:
	v_or_b32_e32 v128, 0x10000, v210
	v_add_u32_e32 v132, 0x10400, v210
	v_add_u32_e32 v136, 0x10800, v210
	v_add_u32_e32 v140, 0x10c00, v210
	v_or_b32_e32 v144, 0x14000, v210
	v_add_u32_e32 v148, 0x14400, v210
	v_add_u32_e32 v152, 0x14800, v210
	v_add_u32_e32 v178, 0x14c00, v210
	ds_read_b128 v[128:131], v128
	ds_read_b128 v[132:135], v132
	ds_read_b128 v[136:139], v136
	ds_read_b128 v[140:143], v140
	ds_read_b128 v[144:147], v144
	ds_read_b128 v[148:151], v148
	ds_read_b128 v[152:155], v152
	ds_read_b128 v[178:181], v178
	s_add_u32 s34, s30, 0xffe00080
	s_addc_u32 s35, s31, -1
	s_cmpk_eq_i32 s71, 0x7c
	s_cselect_b32 s37, s21, s35
	s_cselect_b32 s36, s27, s34
	s_cselect_b32 s35, s19, s70
	s_cselect_b32 s34, s29, s38
	v_lshl_add_u64 v[190:191], s[30:31], 0, v[176:177]
	s_add_i32 m0, s47, 0xc000
	ds_read_b128 v[182:185], v208
	ds_read_b128 v[186:189], v208 offset:1024
	ds_read_b128 v[198:201], v208 offset:2048
	ds_read_b128 v[202:205], v208 offset:3072
	ds_read_b128 v[212:215], v208 offset:4096
	ds_read_b128 v[216:219], v208 offset:5120
	ds_read_b128 v[220:223], v208 offset:6144
	ds_read_b128 v[224:227], v208 offset:7168
	global_load_lds_dwordx4 v[190:191], off
	v_lshl_add_u64 v[190:191], s[30:31], 0, v[174:175]
	s_add_i32 m0, s47, 0xe000
	s_nop 0
	global_load_lds_dwordx4 v[190:191], off
	s_waitcnt vmcnt(8)
	s_waitcnt lgkmcnt(0)
	s_barrier
	s_setprio 1
	s_waitcnt lgkmcnt(0)
	v_mfma_f32_16x16x32_bf16 v[124:127], v[128:131], v[182:185], v[124:127]
	v_mfma_f32_16x16x32_bf16 v[120:123], v[136:139], v[182:185], v[120:123]
	v_mfma_f32_16x16x32_bf16 v[108:111], v[128:131], v[198:201], v[108:111]
	v_mfma_f32_16x16x32_bf16 v[104:107], v[136:139], v[198:201], v[104:107]
	v_mfma_f32_16x16x32_bf16 v[92:95], v[128:131], v[212:215], v[92:95]
	v_mfma_f32_16x16x32_bf16 v[88:91], v[136:139], v[212:215], v[88:91]
	v_mfma_f32_16x16x32_bf16 v[76:79], v[128:131], v[220:223], v[76:79]
	v_mfma_f32_16x16x32_bf16 v[72:75], v[136:139], v[220:223], v[72:75]
	v_mfma_f32_16x16x32_bf16 v[124:127], v[132:135], v[186:189], v[124:127]
	v_mfma_f32_16x16x32_bf16 v[120:123], v[140:143], v[186:189], v[120:123]
	v_mfma_f32_16x16x32_bf16 v[108:111], v[132:135], v[202:205], v[108:111]
	v_mfma_f32_16x16x32_bf16 v[104:107], v[140:143], v[202:205], v[104:107]
	v_mfma_f32_16x16x32_bf16 v[92:95], v[132:135], v[216:219], v[92:95]
	v_mfma_f32_16x16x32_bf16 v[88:91], v[140:143], v[216:219], v[88:91]
	v_mfma_f32_16x16x32_bf16 v[76:79], v[132:135], v[224:227], v[76:79]
	v_mfma_f32_16x16x32_bf16 v[72:75], v[140:143], v[224:227], v[72:75]
	v_mfma_f32_16x16x32_bf16 v[116:119], v[144:147], v[182:185], v[116:119]
	v_mfma_f32_16x16x32_bf16 v[112:115], v[152:155], v[182:185], v[112:115]
	v_mfma_f32_16x16x32_bf16 v[100:103], v[144:147], v[198:201], v[100:103]
	v_mfma_f32_16x16x32_bf16 v[96:99], v[152:155], v[198:201], v[96:99]
	v_mfma_f32_16x16x32_bf16 v[84:87], v[144:147], v[212:215], v[84:87]
	v_mfma_f32_16x16x32_bf16 v[80:83], v[152:155], v[212:215], v[80:83]
	v_mfma_f32_16x16x32_bf16 v[68:71], v[144:147], v[220:223], v[68:71]
	v_mfma_f32_16x16x32_bf16 v[64:67], v[152:155], v[220:223], v[64:67]
	v_mfma_f32_16x16x32_bf16 v[116:119], v[148:151], v[186:189], v[116:119]
	v_mfma_f32_16x16x32_bf16 v[112:115], v[178:181], v[186:189], v[112:115]
	v_mfma_f32_16x16x32_bf16 v[100:103], v[148:151], v[202:205], v[100:103]
	v_mfma_f32_16x16x32_bf16 v[96:99], v[178:181], v[202:205], v[96:99]
	v_mfma_f32_16x16x32_bf16 v[84:87], v[148:151], v[216:219], v[84:87]
	v_mfma_f32_16x16x32_bf16 v[80:83], v[178:181], v[216:219], v[80:83]
	v_mfma_f32_16x16x32_bf16 v[68:71], v[148:151], v[224:227], v[68:71]
	v_mfma_f32_16x16x32_bf16 v[64:67], v[178:181], v[224:227], v[64:67]
	s_setprio 0
	s_barrier
	s_mov_b32 m0, s54
	v_lshl_add_u64 v[190:191], s[34:35], 0, v[160:161]
	s_add_u32 s72, s34, 0x200000
	ds_read_b128 v[182:185], v208 offset:16384
	ds_read_b128 v[186:189], v208 offset:17408
	ds_read_b128 v[198:201], v208 offset:18432
	ds_read_b128 v[202:205], v208 offset:19456
	ds_read_b128 v[212:215], v208 offset:20480
	ds_read_b128 v[216:219], v208 offset:21504
	ds_read_b128 v[220:223], v208 offset:22528
	ds_read_b128 v[224:227], v208 offset:23552
	global_load_lds_dwordx4 v[190:191], off
	v_lshl_add_u64 v[228:229], s[34:35], 0, v[170:171]
	s_mov_b32 m0, s55
	s_addc_u32 s73, s35, 0
	global_load_lds_dwordx4 v[228:229], off
	v_lshl_add_u64 v[230:231], s[72:73], 0, v[160:161]
	s_mov_b32 m0, s56
	v_lshl_add_u64 v[232:233], s[36:37], 0, v[158:159]
	global_load_lds_dwordx4 v[230:231], off
	v_lshl_add_u64 v[230:231], s[72:73], 0, v[170:171]
	s_mov_b32 m0, s57
	s_nop 0
	global_load_lds_dwordx4 v[230:231], off
	v_lshl_add_u64 v[230:231], s[36:37], 0, v[156:157]
	s_mov_b32 m0, s47
	s_nop 0
	global_load_lds_dwordx4 v[230:231], off
	s_mov_b32 m0, s58
	s_nop 0
	global_load_lds_dwordx4 v[232:233], off
	s_waitcnt vmcnt(8)
	s_waitcnt lgkmcnt(0)
	s_barrier
	s_setprio 1
	s_waitcnt lgkmcnt(0)
	v_mfma_f32_16x16x32_bf16 v[60:63], v[128:131], v[182:185], v[60:63]
	v_mfma_f32_16x16x32_bf16 v[56:59], v[136:139], v[182:185], v[56:59]
	v_mfma_f32_16x16x32_bf16 v[44:47], v[128:131], v[198:201], v[44:47]
	v_mfma_f32_16x16x32_bf16 v[40:43], v[136:139], v[198:201], v[40:43]
	v_mfma_f32_16x16x32_bf16 v[28:31], v[128:131], v[212:215], v[28:31]
	v_mfma_f32_16x16x32_bf16 v[24:27], v[136:139], v[212:215], v[24:27]
	v_mfma_f32_16x16x32_bf16 v[12:15], v[128:131], v[220:223], v[12:15]
	v_mfma_f32_16x16x32_bf16 v[8:11], v[136:139], v[220:223], v[8:11]
	v_mfma_f32_16x16x32_bf16 v[60:63], v[132:135], v[186:189], v[60:63]
	v_mfma_f32_16x16x32_bf16 v[56:59], v[140:143], v[186:189], v[56:59]
	v_mfma_f32_16x16x32_bf16 v[44:47], v[132:135], v[202:205], v[44:47]
	v_mfma_f32_16x16x32_bf16 v[40:43], v[140:143], v[202:205], v[40:43]
	v_mfma_f32_16x16x32_bf16 v[28:31], v[132:135], v[216:219], v[28:31]
	v_mfma_f32_16x16x32_bf16 v[24:27], v[140:143], v[216:219], v[24:27]
	v_mfma_f32_16x16x32_bf16 v[12:15], v[132:135], v[224:227], v[12:15]
	v_mfma_f32_16x16x32_bf16 v[8:11], v[140:143], v[224:227], v[8:11]
	v_mfma_f32_16x16x32_bf16 v[52:55], v[144:147], v[182:185], v[52:55]
	v_mfma_f32_16x16x32_bf16 v[48:51], v[152:155], v[182:185], v[48:51]
	v_mfma_f32_16x16x32_bf16 v[36:39], v[144:147], v[198:201], v[36:39]
	v_mfma_f32_16x16x32_bf16 v[32:35], v[152:155], v[198:201], v[32:35]
	v_mfma_f32_16x16x32_bf16 v[20:23], v[144:147], v[212:215], v[20:23]
	v_mfma_f32_16x16x32_bf16 v[16:19], v[152:155], v[212:215], v[16:19]
	v_mfma_f32_16x16x32_bf16 v[4:7], v[144:147], v[220:223], v[4:7]
	v_mfma_f32_16x16x32_bf16 v[0:3], v[152:155], v[220:223], v[0:3]
	v_mfma_f32_16x16x32_bf16 v[52:55], v[148:151], v[186:189], v[52:55]
	v_mfma_f32_16x16x32_bf16 v[48:51], v[178:181], v[186:189], v[48:51]
	v_mfma_f32_16x16x32_bf16 v[36:39], v[148:151], v[202:205], v[36:39]
	v_mfma_f32_16x16x32_bf16 v[32:35], v[178:181], v[202:205], v[32:35]
	v_mfma_f32_16x16x32_bf16 v[20:23], v[148:151], v[216:219], v[20:23]
	v_mfma_f32_16x16x32_bf16 v[16:19], v[178:181], v[216:219], v[16:19]
	v_mfma_f32_16x16x32_bf16 v[4:7], v[148:151], v[224:227], v[4:7]
	v_mfma_f32_16x16x32_bf16 v[0:3], v[178:181], v[224:227], v[0:3]
	s_setprio 0
	s_barrier
	v_or_b32_e32 v128, 0x18000, v210
	v_add_u32_e32 v132, 0x18400, v210
	v_add_u32_e32 v136, 0x18800, v210
	v_add_u32_e32 v140, 0x18c00, v210
	v_or_b32_e32 v144, 0x1c000, v210
	v_add_u32_e32 v148, 0x1c400, v210
	v_add_u32_e32 v152, 0x1c800, v210
	v_add_u32_e32 v178, 0x1cc00, v210
	ds_read_b128 v[128:131], v128
	ds_read_b128 v[132:135], v132
	ds_read_b128 v[136:139], v136
	ds_read_b128 v[140:143], v140
	ds_read_b128 v[144:147], v144
	ds_read_b128 v[148:151], v148
	ds_read_b128 v[152:155], v152
	ds_read_b128 v[178:181], v178
	s_add_u32 s36, s36, 0x200000
	s_addc_u32 s37, s37, 0
	s_mov_b32 m0, s59
	v_lshl_add_u64 v[234:235], s[36:37], 0, v[156:157]
	ds_read_b128 v[182:185], v208 offset:32768
	ds_read_b128 v[186:189], v208 offset:33792
	ds_read_b128 v[198:201], v208 offset:34816
	ds_read_b128 v[202:205], v208 offset:35840
	ds_read_b128 v[212:215], v208 offset:36864
	ds_read_b128 v[216:219], v208 offset:37888
	ds_read_b128 v[220:223], v208 offset:38912
	ds_read_b128 v[224:227], v208 offset:39936
	global_load_lds_dwordx4 v[234:235], off
	v_lshl_add_u64 v[234:235], s[36:37], 0, v[158:159]
	s_mov_b32 m0, s60
	s_nop 0
	global_load_lds_dwordx4 v[234:235], off
	s_waitcnt vmcnt(8)
	s_waitcnt lgkmcnt(0)
	s_barrier
	s_setprio 1
	s_waitcnt lgkmcnt(0)
	v_mfma_f32_16x16x32_bf16 v[124:127], v[128:131], v[182:185], v[124:127]
	v_mfma_f32_16x16x32_bf16 v[120:123], v[136:139], v[182:185], v[120:123]
	v_mfma_f32_16x16x32_bf16 v[108:111], v[128:131], v[198:201], v[108:111]
	v_mfma_f32_16x16x32_bf16 v[104:107], v[136:139], v[198:201], v[104:107]
	v_mfma_f32_16x16x32_bf16 v[92:95], v[128:131], v[212:215], v[92:95]
	v_mfma_f32_16x16x32_bf16 v[88:91], v[136:139], v[212:215], v[88:91]
	v_mfma_f32_16x16x32_bf16 v[76:79], v[128:131], v[220:223], v[76:79]
	v_mfma_f32_16x16x32_bf16 v[72:75], v[136:139], v[220:223], v[72:75]
	v_mfma_f32_16x16x32_bf16 v[124:127], v[132:135], v[186:189], v[124:127]
	v_mfma_f32_16x16x32_bf16 v[120:123], v[140:143], v[186:189], v[120:123]
	v_mfma_f32_16x16x32_bf16 v[108:111], v[132:135], v[202:205], v[108:111]
	v_mfma_f32_16x16x32_bf16 v[104:107], v[140:143], v[202:205], v[104:107]
	v_mfma_f32_16x16x32_bf16 v[92:95], v[132:135], v[216:219], v[92:95]
	v_mfma_f32_16x16x32_bf16 v[88:91], v[140:143], v[216:219], v[88:91]
	v_mfma_f32_16x16x32_bf16 v[76:79], v[132:135], v[224:227], v[76:79]
	v_mfma_f32_16x16x32_bf16 v[72:75], v[140:143], v[224:227], v[72:75]
	v_mfma_f32_16x16x32_bf16 v[116:119], v[144:147], v[182:185], v[116:119]
	v_mfma_f32_16x16x32_bf16 v[112:115], v[152:155], v[182:185], v[112:115]
	v_mfma_f32_16x16x32_bf16 v[100:103], v[144:147], v[198:201], v[100:103]
	v_mfma_f32_16x16x32_bf16 v[96:99], v[152:155], v[198:201], v[96:99]
	v_mfma_f32_16x16x32_bf16 v[84:87], v[144:147], v[212:215], v[84:87]
	v_mfma_f32_16x16x32_bf16 v[80:83], v[152:155], v[212:215], v[80:83]
	v_mfma_f32_16x16x32_bf16 v[68:71], v[144:147], v[220:223], v[68:71]
	v_mfma_f32_16x16x32_bf16 v[64:67], v[152:155], v[220:223], v[64:67]
	v_mfma_f32_16x16x32_bf16 v[116:119], v[148:151], v[186:189], v[116:119]
	v_mfma_f32_16x16x32_bf16 v[112:115], v[178:181], v[186:189], v[112:115]
	v_mfma_f32_16x16x32_bf16 v[100:103], v[148:151], v[202:205], v[100:103]
	v_mfma_f32_16x16x32_bf16 v[96:99], v[178:181], v[202:205], v[96:99]
	v_mfma_f32_16x16x32_bf16 v[84:87], v[148:151], v[216:219], v[84:87]
	v_mfma_f32_16x16x32_bf16 v[80:83], v[178:181], v[216:219], v[80:83]
	v_mfma_f32_16x16x32_bf16 v[68:71], v[148:151], v[224:227], v[68:71]
	v_mfma_f32_16x16x32_bf16 v[64:67], v[178:181], v[224:227], v[64:67]
	s_setprio 0
	s_barrier
	s_mov_b32 m0, s62
	v_lshl_add_u64 v[190:191], v[190:191], 0, s[40:41]
	s_add_u32 s34, s34, 0x200080
	ds_read_b128 v[182:185], v208 offset:49152
	ds_read_b128 v[186:189], v208 offset:50176
	ds_read_b128 v[198:201], v208 offset:51200
	ds_read_b128 v[202:205], v208 offset:52224
	ds_read_b128 v[212:215], v208 offset:53248
	ds_read_b128 v[216:219], v208 offset:54272
	ds_read_b128 v[220:223], v208 offset:55296
	ds_read_b128 v[224:227], v208 offset:56320
	global_load_lds_dwordx4 v[190:191], off
	v_lshl_add_u64 v[190:191], v[228:229], 0, s[40:41]
	s_mov_b32 m0, s63
	s_addc_u32 s35, s35, 0
	global_load_lds_dwordx4 v[190:191], off
	v_lshl_add_u64 v[190:191], s[34:35], 0, v[160:161]
	s_mov_b32 m0, s66
	s_nop 0
	global_load_lds_dwordx4 v[190:191], off
	v_lshl_add_u64 v[190:191], s[34:35], 0, v[170:171]
	s_mov_b32 m0, s67
	s_nop 0
	global_load_lds_dwordx4 v[190:191], off
	v_lshl_add_u64 v[190:191], v[230:231], 0, s[40:41]
	s_mov_b32 m0, s64
	s_nop 0
	global_load_lds_dwordx4 v[190:191], off
	v_lshl_add_u64 v[190:191], v[232:233], 0, s[40:41]
	s_mov_b32 m0, s65
	s_nop 0
	global_load_lds_dwordx4 v[190:191], off
	s_waitcnt vmcnt(8)
	s_waitcnt lgkmcnt(0)
	s_barrier
	s_setprio 1
	s_waitcnt lgkmcnt(0)
	v_mfma_f32_16x16x32_bf16 v[60:63], v[128:131], v[182:185], v[60:63]
	v_mfma_f32_16x16x32_bf16 v[56:59], v[136:139], v[182:185], v[56:59]
	v_mfma_f32_16x16x32_bf16 v[44:47], v[128:131], v[198:201], v[44:47]
	v_mfma_f32_16x16x32_bf16 v[40:43], v[136:139], v[198:201], v[40:43]
	v_mfma_f32_16x16x32_bf16 v[28:31], v[128:131], v[212:215], v[28:31]
	v_mfma_f32_16x16x32_bf16 v[24:27], v[136:139], v[212:215], v[24:27]
	v_mfma_f32_16x16x32_bf16 v[12:15], v[128:131], v[220:223], v[12:15]
	v_mfma_f32_16x16x32_bf16 v[8:11], v[136:139], v[220:223], v[8:11]
	v_mfma_f32_16x16x32_bf16 v[60:63], v[132:135], v[186:189], v[60:63]
	v_mfma_f32_16x16x32_bf16 v[56:59], v[140:143], v[186:189], v[56:59]
	v_mfma_f32_16x16x32_bf16 v[44:47], v[132:135], v[202:205], v[44:47]
	v_mfma_f32_16x16x32_bf16 v[40:43], v[140:143], v[202:205], v[40:43]
	v_mfma_f32_16x16x32_bf16 v[28:31], v[132:135], v[216:219], v[28:31]
	v_mfma_f32_16x16x32_bf16 v[24:27], v[140:143], v[216:219], v[24:27]
	v_mfma_f32_16x16x32_bf16 v[12:15], v[132:135], v[224:227], v[12:15]
	v_mfma_f32_16x16x32_bf16 v[8:11], v[140:143], v[224:227], v[8:11]
	v_mfma_f32_16x16x32_bf16 v[52:55], v[144:147], v[182:185], v[52:55]
	v_mfma_f32_16x16x32_bf16 v[48:51], v[152:155], v[182:185], v[48:51]
	v_mfma_f32_16x16x32_bf16 v[36:39], v[144:147], v[198:201], v[36:39]
	v_mfma_f32_16x16x32_bf16 v[32:35], v[152:155], v[198:201], v[32:35]
	v_mfma_f32_16x16x32_bf16 v[20:23], v[144:147], v[212:215], v[20:23]
	v_mfma_f32_16x16x32_bf16 v[16:19], v[152:155], v[212:215], v[16:19]
	v_mfma_f32_16x16x32_bf16 v[4:7], v[144:147], v[220:223], v[4:7]
	v_mfma_f32_16x16x32_bf16 v[0:3], v[152:155], v[220:223], v[0:3]
	v_mfma_f32_16x16x32_bf16 v[52:55], v[148:151], v[186:189], v[52:55]
	v_mfma_f32_16x16x32_bf16 v[48:51], v[178:181], v[186:189], v[48:51]
	v_mfma_f32_16x16x32_bf16 v[36:39], v[148:151], v[202:205], v[36:39]
	v_mfma_f32_16x16x32_bf16 v[32:35], v[178:181], v[202:205], v[32:35]
	v_mfma_f32_16x16x32_bf16 v[20:23], v[148:151], v[216:219], v[20:23]
	v_mfma_f32_16x16x32_bf16 v[16:19], v[178:181], v[216:219], v[16:19]
	v_mfma_f32_16x16x32_bf16 v[4:7], v[148:151], v[224:227], v[4:7]
	v_mfma_f32_16x16x32_bf16 v[0:3], v[178:181], v[224:227], v[0:3]
	s_setprio 0
	s_barrier
	s_add_i32 s71, s71, 2
	s_add_u32 s38, s38, 0x100
	s_addc_u32 s70, s70, 0
	s_add_u32 s30, s30, 0x100
	s_addc_u32 s31, s31, 0
	s_cmpk_gt_u32 s71, 0x7d
	s_cbranch_scc0 .LBB0_916
	s_and_b64 vcc, exec, s[16:17]
	s_cbranch_vccz .LBB0_919
	s_barrier

.LBB0_958:
	v_or_b32_e32 v128, 0x10000, v183
	v_add_u32_e32 v132, 0x10400, v183
	v_add_u32_e32 v136, 0x10800, v183
	v_add_u32_e32 v140, 0x10c00, v183
	v_or_b32_e32 v144, 0x14000, v183
	v_add_u32_e32 v170, 0x14400, v183
	v_add_u32_e32 v174, 0x14800, v183
	ds_read_b128 v[128:131], v128
	ds_read_b128 v[132:135], v132
	ds_read_b128 v[136:139], v136
	ds_read_b128 v[140:143], v140
	ds_read_b128 v[144:147], v144
	ds_read_b128 v[170:173], v170
	v_add_u32_e32 v176, 0x14c00, v183
	ds_read_b128 v[184:187], v174
	ds_read_b128 v[198:201], v176
	s_add_u32 s24, s22, 0xffe00080
	s_addc_u32 s25, s23, -1
	s_cmpk_eq_i32 s64, 0x7c
	s_cselect_b32 s27, s15, s25
	s_cselect_b32 s26, s60, s24
	s_cselect_b32 s25, s13, s63
	s_cselect_b32 s24, s61, s62
	v_lshl_add_u64 v[176:177], s[22:23], 0, v[158:159]
	s_add_i32 m0, s36, 0xc000
	ds_read_b128 v[202:205], v179
	ds_read_b128 v[210:213], v179 offset:1024
	ds_read_b128 v[214:217], v179 offset:2048
	ds_read_b128 v[218:221], v179 offset:3072
	ds_read_b128 v[222:225], v179 offset:4096
	ds_read_b128 v[226:229], v179 offset:5120
	ds_read_b128 v[230:233], v179 offset:6144
	ds_read_b128 v[240:243], v179 offset:7168
	global_load_lds_dwordx4 v[176:177], off
	v_lshl_add_u64 v[176:177], s[22:23], 0, v[156:157]
	s_add_i32 m0, s36, 0xe000
	s_nop 0
	global_load_lds_dwordx4 v[176:177], off
	s_waitcnt vmcnt(8)
	s_waitcnt lgkmcnt(0)
	s_barrier
	s_setprio 1
	s_waitcnt lgkmcnt(0)
	v_mfma_f32_16x16x32_bf16 v[124:127], v[128:131], v[202:205], v[124:127]
	v_mfma_f32_16x16x32_bf16 v[120:123], v[136:139], v[202:205], v[120:123]
	v_mfma_f32_16x16x32_bf16 v[108:111], v[128:131], v[214:217], v[108:111]
	v_mfma_f32_16x16x32_bf16 v[104:107], v[136:139], v[214:217], v[104:107]
	v_mfma_f32_16x16x32_bf16 v[96:99], v[128:131], v[222:225], v[96:99]
	v_mfma_f32_16x16x32_bf16 v[88:91], v[136:139], v[222:225], v[88:91]
	v_mfma_f32_16x16x32_bf16 v[80:83], v[128:131], v[230:233], v[80:83]
	v_mfma_f32_16x16x32_bf16 v[72:75], v[136:139], v[230:233], v[72:75]
	v_mfma_f32_16x16x32_bf16 v[124:127], v[132:135], v[210:213], v[124:127]
	v_mfma_f32_16x16x32_bf16 v[120:123], v[140:143], v[210:213], v[120:123]
	v_mfma_f32_16x16x32_bf16 v[108:111], v[132:135], v[218:221], v[108:111]
	v_mfma_f32_16x16x32_bf16 v[104:107], v[140:143], v[218:221], v[104:107]
	v_mfma_f32_16x16x32_bf16 v[96:99], v[132:135], v[226:229], v[96:99]
	v_mfma_f32_16x16x32_bf16 v[88:91], v[140:143], v[226:229], v[88:91]
	v_mfma_f32_16x16x32_bf16 v[80:83], v[132:135], v[240:243], v[80:83]
	v_mfma_f32_16x16x32_bf16 v[72:75], v[140:143], v[240:243], v[72:75]
	v_mfma_f32_16x16x32_bf16 v[116:119], v[144:147], v[202:205], v[116:119]
	v_mfma_f32_16x16x32_bf16 v[112:115], v[184:187], v[202:205], v[112:115]
	v_mfma_f32_16x16x32_bf16 v[100:103], v[144:147], v[214:217], v[100:103]
	v_mfma_f32_16x16x32_bf16 v[92:95], v[184:187], v[214:217], v[92:95]
	v_mfma_f32_16x16x32_bf16 v[84:87], v[144:147], v[222:225], v[84:87]
	v_mfma_f32_16x16x32_bf16 v[76:79], v[184:187], v[222:225], v[76:79]
	v_mfma_f32_16x16x32_bf16 v[68:71], v[144:147], v[230:233], v[68:71]
	v_mfma_f32_16x16x32_bf16 v[64:67], v[184:187], v[230:233], v[64:67]
	v_mfma_f32_16x16x32_bf16 v[116:119], v[170:173], v[210:213], v[116:119]
	v_mfma_f32_16x16x32_bf16 v[112:115], v[198:201], v[210:213], v[112:115]
	v_mfma_f32_16x16x32_bf16 v[100:103], v[170:173], v[218:221], v[100:103]
	v_mfma_f32_16x16x32_bf16 v[92:95], v[198:201], v[218:221], v[92:95]
	v_mfma_f32_16x16x32_bf16 v[84:87], v[170:173], v[226:229], v[84:87]
	v_mfma_f32_16x16x32_bf16 v[76:79], v[198:201], v[226:229], v[76:79]
	v_mfma_f32_16x16x32_bf16 v[68:71], v[170:173], v[240:243], v[68:71]
	v_mfma_f32_16x16x32_bf16 v[64:67], v[198:201], v[240:243], v[64:67]
	s_setprio 0
	s_barrier
	s_mov_b32 m0, s37
	v_lshl_add_u64 v[176:177], s[24:25], 0, v[160:161]
	s_add_u32 s66, s24, 0x200000
	ds_read_b128 v[202:205], v179 offset:16384
	ds_read_b128 v[210:213], v179 offset:17408
	ds_read_b128 v[214:217], v179 offset:18432
	ds_read_b128 v[218:221], v179 offset:19456
	ds_read_b128 v[222:225], v179 offset:20480
	ds_read_b128 v[226:229], v179 offset:21504
	ds_read_b128 v[230:233], v179 offset:22528
	ds_read_b128 v[240:243], v179 offset:23552
	global_load_lds_dwordx4 v[176:177], off
	v_lshl_add_u64 v[180:181], s[24:25], 0, v[152:153]
	s_mov_b32 m0, s38
	s_addc_u32 s67, s25, 0
	global_load_lds_dwordx4 v[180:181], off
	v_lshl_add_u64 v[190:191], s[66:67], 0, v[160:161]
	s_mov_b32 m0, s42
	v_lshl_add_u64 v[206:207], s[26:27], 0, v[150:151]
	global_load_lds_dwordx4 v[190:191], off
	v_lshl_add_u64 v[190:191], s[66:67], 0, v[152:153]
	s_mov_b32 m0, s43
	s_nop 0
	global_load_lds_dwordx4 v[190:191], off
	v_lshl_add_u64 v[190:191], s[26:27], 0, v[148:149]
	s_mov_b32 m0, s36
	s_nop 0
	global_load_lds_dwordx4 v[190:191], off
	s_mov_b32 m0, s44
	s_nop 0
	global_load_lds_dwordx4 v[206:207], off
	s_waitcnt vmcnt(8)
	s_waitcnt lgkmcnt(0)
	s_barrier
	s_setprio 1
	s_waitcnt lgkmcnt(0)
	v_mfma_f32_16x16x32_bf16 v[60:63], v[128:131], v[202:205], v[60:63]
	v_mfma_f32_16x16x32_bf16 v[56:59], v[136:139], v[202:205], v[56:59]
	v_mfma_f32_16x16x32_bf16 v[48:51], v[128:131], v[214:217], v[48:51]
	v_mfma_f32_16x16x32_bf16 v[40:43], v[136:139], v[214:217], v[40:43]
	v_mfma_f32_16x16x32_bf16 v[32:35], v[128:131], v[222:225], v[32:35]
	v_mfma_f32_16x16x32_bf16 v[24:27], v[136:139], v[222:225], v[24:27]
	v_mfma_f32_16x16x32_bf16 v[16:19], v[128:131], v[230:233], v[16:19]
	v_mfma_f32_16x16x32_bf16 v[8:11], v[136:139], v[230:233], v[8:11]
	v_mfma_f32_16x16x32_bf16 v[60:63], v[132:135], v[210:213], v[60:63]
	v_mfma_f32_16x16x32_bf16 v[56:59], v[140:143], v[210:213], v[56:59]
	v_mfma_f32_16x16x32_bf16 v[48:51], v[132:135], v[218:221], v[48:51]
	v_mfma_f32_16x16x32_bf16 v[40:43], v[140:143], v[218:221], v[40:43]
	v_mfma_f32_16x16x32_bf16 v[32:35], v[132:135], v[226:229], v[32:35]
	v_mfma_f32_16x16x32_bf16 v[24:27], v[140:143], v[226:229], v[24:27]
	v_mfma_f32_16x16x32_bf16 v[16:19], v[132:135], v[240:243], v[16:19]
	v_mfma_f32_16x16x32_bf16 v[8:11], v[140:143], v[240:243], v[8:11]
	v_mfma_f32_16x16x32_bf16 v[52:55], v[144:147], v[202:205], v[52:55]
	v_mfma_f32_16x16x32_bf16 v[44:47], v[184:187], v[202:205], v[44:47]
	v_mfma_f32_16x16x32_bf16 v[36:39], v[144:147], v[214:217], v[36:39]
	v_mfma_f32_16x16x32_bf16 v[28:31], v[184:187], v[214:217], v[28:31]
	v_mfma_f32_16x16x32_bf16 v[20:23], v[144:147], v[222:225], v[20:23]
	v_mfma_f32_16x16x32_bf16 v[12:15], v[184:187], v[222:225], v[12:15]
	v_mfma_f32_16x16x32_bf16 v[4:7], v[144:147], v[230:233], v[4:7]
	v_mfma_f32_16x16x32_bf16 v[0:3], v[184:187], v[230:233], v[0:3]
	v_mfma_f32_16x16x32_bf16 v[52:55], v[170:173], v[210:213], v[52:55]
	v_mfma_f32_16x16x32_bf16 v[44:47], v[198:201], v[210:213], v[44:47]
	v_mfma_f32_16x16x32_bf16 v[36:39], v[170:173], v[218:221], v[36:39]
	v_mfma_f32_16x16x32_bf16 v[28:31], v[198:201], v[218:221], v[28:31]
	v_mfma_f32_16x16x32_bf16 v[20:23], v[170:173], v[226:229], v[20:23]
	v_mfma_f32_16x16x32_bf16 v[12:15], v[198:201], v[226:229], v[12:15]
	v_mfma_f32_16x16x32_bf16 v[4:7], v[170:173], v[240:243], v[4:7]
	v_mfma_f32_16x16x32_bf16 v[0:3], v[198:201], v[240:243], v[0:3]
	s_setprio 0
	s_barrier
	v_or_b32_e32 v128, 0x18000, v183
	v_add_u32_e32 v132, 0x18400, v183
	v_add_u32_e32 v136, 0x18800, v183
	v_add_u32_e32 v140, 0x18c00, v183
	v_or_b32_e32 v144, 0x1c000, v183
	v_add_u32_e32 v170, 0x1c400, v183
	v_add_u32_e32 v174, 0x1c800, v183
	ds_read_b128 v[128:131], v128
	ds_read_b128 v[132:135], v132
	ds_read_b128 v[136:139], v136
	ds_read_b128 v[140:143], v140
	ds_read_b128 v[144:147], v144
	ds_read_b128 v[170:173], v170
	v_add_u32_e32 v178, 0x1cc00, v183
	ds_read_b128 v[184:187], v174
	ds_read_b128 v[198:201], v178
	s_add_u32 s26, s26, 0x200000
	s_addc_u32 s27, s27, 0
	s_mov_b32 m0, s45
	v_lshl_add_u64 v[208:209], s[26:27], 0, v[148:149]
	ds_read_b128 v[202:205], v179 offset:32768
	ds_read_b128 v[210:213], v179 offset:33792
	ds_read_b128 v[214:217], v179 offset:34816
	ds_read_b128 v[218:221], v179 offset:35840
	ds_read_b128 v[222:225], v179 offset:36864
	ds_read_b128 v[226:229], v179 offset:37888
	ds_read_b128 v[230:233], v179 offset:38912
	ds_read_b128 v[240:243], v179 offset:39936
	global_load_lds_dwordx4 v[208:209], off
	v_lshl_add_u64 v[208:209], s[26:27], 0, v[150:151]
	s_mov_b32 m0, s46
	s_nop 0
	global_load_lds_dwordx4 v[208:209], off
	s_waitcnt vmcnt(8)
	s_waitcnt lgkmcnt(0)
	s_barrier
	s_setprio 1
	s_waitcnt lgkmcnt(0)
	v_mfma_f32_16x16x32_bf16 v[124:127], v[128:131], v[202:205], v[124:127]
	v_mfma_f32_16x16x32_bf16 v[120:123], v[136:139], v[202:205], v[120:123]
	v_mfma_f32_16x16x32_bf16 v[108:111], v[128:131], v[214:217], v[108:111]
	v_mfma_f32_16x16x32_bf16 v[104:107], v[136:139], v[214:217], v[104:107]
	v_mfma_f32_16x16x32_bf16 v[96:99], v[128:131], v[222:225], v[96:99]
	v_mfma_f32_16x16x32_bf16 v[88:91], v[136:139], v[222:225], v[88:91]
	v_mfma_f32_16x16x32_bf16 v[80:83], v[128:131], v[230:233], v[80:83]
	v_mfma_f32_16x16x32_bf16 v[72:75], v[136:139], v[230:233], v[72:75]
	v_mfma_f32_16x16x32_bf16 v[124:127], v[132:135], v[210:213], v[124:127]
	v_mfma_f32_16x16x32_bf16 v[120:123], v[140:143], v[210:213], v[120:123]
	v_mfma_f32_16x16x32_bf16 v[108:111], v[132:135], v[218:221], v[108:111]
	v_mfma_f32_16x16x32_bf16 v[104:107], v[140:143], v[218:221], v[104:107]
	v_mfma_f32_16x16x32_bf16 v[96:99], v[132:135], v[226:229], v[96:99]
	v_mfma_f32_16x16x32_bf16 v[88:91], v[140:143], v[226:229], v[88:91]
	v_mfma_f32_16x16x32_bf16 v[80:83], v[132:135], v[240:243], v[80:83]
	v_mfma_f32_16x16x32_bf16 v[72:75], v[140:143], v[240:243], v[72:75]
	v_mfma_f32_16x16x32_bf16 v[116:119], v[144:147], v[202:205], v[116:119]
	v_mfma_f32_16x16x32_bf16 v[112:115], v[184:187], v[202:205], v[112:115]
	v_mfma_f32_16x16x32_bf16 v[100:103], v[144:147], v[214:217], v[100:103]
	v_mfma_f32_16x16x32_bf16 v[92:95], v[184:187], v[214:217], v[92:95]
	v_mfma_f32_16x16x32_bf16 v[84:87], v[144:147], v[222:225], v[84:87]
	v_mfma_f32_16x16x32_bf16 v[76:79], v[184:187], v[222:225], v[76:79]
	v_mfma_f32_16x16x32_bf16 v[68:71], v[144:147], v[230:233], v[68:71]
	v_mfma_f32_16x16x32_bf16 v[64:67], v[184:187], v[230:233], v[64:67]
	v_mfma_f32_16x16x32_bf16 v[116:119], v[170:173], v[210:213], v[116:119]
	v_mfma_f32_16x16x32_bf16 v[112:115], v[198:201], v[210:213], v[112:115]
	v_mfma_f32_16x16x32_bf16 v[100:103], v[170:173], v[218:221], v[100:103]
	v_mfma_f32_16x16x32_bf16 v[92:95], v[198:201], v[218:221], v[92:95]
	v_mfma_f32_16x16x32_bf16 v[84:87], v[170:173], v[226:229], v[84:87]
	v_mfma_f32_16x16x32_bf16 v[76:79], v[198:201], v[226:229], v[76:79]
	v_mfma_f32_16x16x32_bf16 v[68:71], v[170:173], v[240:243], v[68:71]
	v_mfma_f32_16x16x32_bf16 v[64:67], v[198:201], v[240:243], v[64:67]
	s_setprio 0
	s_barrier
	s_mov_b32 m0, s47
	v_lshl_add_u64 v[176:177], v[176:177], 0, s[40:41]
	s_add_u32 s24, s24, 0x200080
	ds_read_b128 v[202:205], v179 offset:49152
	ds_read_b128 v[210:213], v179 offset:50176
	ds_read_b128 v[214:217], v179 offset:51200
	ds_read_b128 v[218:221], v179 offset:52224
	ds_read_b128 v[222:225], v179 offset:53248
	ds_read_b128 v[226:229], v179 offset:54272
	ds_read_b128 v[230:233], v179 offset:55296
	ds_read_b128 v[240:243], v179 offset:56320
	global_load_lds_dwordx4 v[176:177], off
	v_lshl_add_u64 v[176:177], v[180:181], 0, s[40:41]
	s_mov_b32 m0, s54
	s_addc_u32 s25, s25, 0
	global_load_lds_dwordx4 v[176:177], off
	v_lshl_add_u64 v[176:177], s[24:25], 0, v[160:161]
	s_mov_b32 m0, s57
	s_nop 0
	global_load_lds_dwordx4 v[176:177], off
	v_lshl_add_u64 v[176:177], s[24:25], 0, v[152:153]
	s_mov_b32 m0, s58
	s_nop 0
	global_load_lds_dwordx4 v[176:177], off
	v_lshl_add_u64 v[176:177], v[190:191], 0, s[40:41]
	s_mov_b32 m0, s55
	s_nop 0
	global_load_lds_dwordx4 v[176:177], off
	v_lshl_add_u64 v[176:177], v[206:207], 0, s[40:41]
	s_mov_b32 m0, s56
	s_nop 0
	global_load_lds_dwordx4 v[176:177], off
	s_waitcnt vmcnt(8)
	s_waitcnt lgkmcnt(0)
	s_barrier
	s_setprio 1
	s_waitcnt lgkmcnt(0)
	v_mfma_f32_16x16x32_bf16 v[60:63], v[128:131], v[202:205], v[60:63]
	v_mfma_f32_16x16x32_bf16 v[56:59], v[136:139], v[202:205], v[56:59]
	v_mfma_f32_16x16x32_bf16 v[48:51], v[128:131], v[214:217], v[48:51]
	v_mfma_f32_16x16x32_bf16 v[40:43], v[136:139], v[214:217], v[40:43]
	v_mfma_f32_16x16x32_bf16 v[32:35], v[128:131], v[222:225], v[32:35]
	v_mfma_f32_16x16x32_bf16 v[24:27], v[136:139], v[222:225], v[24:27]
	v_mfma_f32_16x16x32_bf16 v[16:19], v[128:131], v[230:233], v[16:19]
	v_mfma_f32_16x16x32_bf16 v[8:11], v[136:139], v[230:233], v[8:11]
	v_mfma_f32_16x16x32_bf16 v[60:63], v[132:135], v[210:213], v[60:63]
	v_mfma_f32_16x16x32_bf16 v[56:59], v[140:143], v[210:213], v[56:59]
	v_mfma_f32_16x16x32_bf16 v[48:51], v[132:135], v[218:221], v[48:51]
	v_mfma_f32_16x16x32_bf16 v[40:43], v[140:143], v[218:221], v[40:43]
	v_mfma_f32_16x16x32_bf16 v[32:35], v[132:135], v[226:229], v[32:35]
	v_mfma_f32_16x16x32_bf16 v[24:27], v[140:143], v[226:229], v[24:27]
	v_mfma_f32_16x16x32_bf16 v[16:19], v[132:135], v[240:243], v[16:19]
	v_mfma_f32_16x16x32_bf16 v[8:11], v[140:143], v[240:243], v[8:11]
	v_mfma_f32_16x16x32_bf16 v[52:55], v[144:147], v[202:205], v[52:55]
	v_mfma_f32_16x16x32_bf16 v[44:47], v[184:187], v[202:205], v[44:47]
	v_mfma_f32_16x16x32_bf16 v[36:39], v[144:147], v[214:217], v[36:39]
	v_mfma_f32_16x16x32_bf16 v[28:31], v[184:187], v[214:217], v[28:31]
	v_mfma_f32_16x16x32_bf16 v[20:23], v[144:147], v[222:225], v[20:23]
	v_mfma_f32_16x16x32_bf16 v[12:15], v[184:187], v[222:225], v[12:15]
	v_mfma_f32_16x16x32_bf16 v[4:7], v[144:147], v[230:233], v[4:7]
	v_mfma_f32_16x16x32_bf16 v[0:3], v[184:187], v[230:233], v[0:3]
	v_mfma_f32_16x16x32_bf16 v[52:55], v[170:173], v[210:213], v[52:55]
	v_mfma_f32_16x16x32_bf16 v[44:47], v[198:201], v[210:213], v[44:47]
	v_mfma_f32_16x16x32_bf16 v[36:39], v[170:173], v[218:221], v[36:39]
	v_mfma_f32_16x16x32_bf16 v[28:31], v[198:201], v[218:221], v[28:31]
	v_mfma_f32_16x16x32_bf16 v[20:23], v[170:173], v[226:229], v[20:23]
	v_mfma_f32_16x16x32_bf16 v[12:15], v[198:201], v[226:229], v[12:15]
	v_mfma_f32_16x16x32_bf16 v[4:7], v[170:173], v[240:243], v[4:7]
	v_mfma_f32_16x16x32_bf16 v[0:3], v[198:201], v[240:243], v[0:3]
	s_setprio 0
	s_barrier
	s_add_i32 s64, s64, 2
	s_add_u32 s62, s62, 0x100
	s_addc_u32 s63, s63, 0
	s_add_u32 s22, s22, 0x100
	s_addc_u32 s23, s23, 0
	s_cmpk_gt_u32 s64, 0x7d
	s_cbranch_scc0 .LBB0_958
	v_readlane_b32 s62, v253, 42
	s_and_b64 vcc, exec, s[10:11]
	s_movk_i32 s60, 0x2000
	v_readlane_b32 s63, v253, 43
	s_cbranch_vccz .LBB0_961
	s_barrier

.LBB0_1081:
	v_or_b32_e32 v112, 0x10000, v189
	v_add_u32_e32 v116, 0x10400, v189
	v_add_u32_e32 v128, 0x10800, v189
	v_add_u32_e32 v140, 0x10c00, v189
	v_or_b32_e32 v144, 0x14000, v189
	v_add_u32_e32 v148, 0x14400, v189
	v_add_u32_e32 v172, 0x14800, v189
	v_add_u32_e32 v176, 0x14c00, v189
	ds_read_b128 v[112:115], v112
	ds_read_b128 v[116:119], v116
	ds_read_b128 v[128:131], v128
	ds_read_b128 v[140:143], v140
	ds_read_b128 v[144:147], v144
	ds_read_b128 v[148:151], v148
	ds_read_b128 v[172:175], v172
	ds_read_b128 v[176:179], v176
	s_add_u32 s28, s26, 0xfff80080
	s_addc_u32 s29, s27, -1
	s_cmp_eq_u32 s67, 28
	s_cselect_b32 s31, s17, s29
	s_cselect_b32 s30, s23, s28
	s_cselect_b32 s29, s15, s66
	s_cselect_b32 s28, s25, s38
	v_lshl_add_u64 v[182:183], s[26:27], 0, v[170:171]
	s_add_i32 m0, s43, 0xc000
	ds_read_b128 v[198:201], v185
	ds_read_b128 v[210:213], v185 offset:1024
	ds_read_b128 v[214:217], v185 offset:2048
	ds_read_b128 v[218:221], v185 offset:3072
	ds_read_b128 v[222:225], v185 offset:4096
	ds_read_b128 v[226:229], v185 offset:5120
	ds_read_b128 v[230:233], v185 offset:6144
	ds_read_b128 v[244:247], v185 offset:7168
	global_load_lds_dwordx4 v[182:183], off
	v_lshl_add_u64 v[182:183], s[26:27], 0, v[158:159]
	s_add_i32 m0, s43, 0xe000
	s_nop 0
	global_load_lds_dwordx4 v[182:183], off
	s_waitcnt vmcnt(8)
	s_waitcnt lgkmcnt(0)
	s_barrier
	s_setprio 1
	s_waitcnt lgkmcnt(0)
	v_mfma_f32_16x16x32_bf16 v[136:139], v[112:115], v[198:201], v[136:139]
	v_mfma_f32_16x16x32_bf16 v[132:135], v[128:131], v[198:201], v[132:135]
	v_mfma_f32_16x16x32_bf16 v[108:111], v[112:115], v[214:217], v[108:111]
	v_mfma_f32_16x16x32_bf16 v[104:107], v[128:131], v[214:217], v[104:107]
	v_mfma_f32_16x16x32_bf16 v[92:95], v[112:115], v[222:225], v[92:95]
	v_mfma_f32_16x16x32_bf16 v[88:91], v[128:131], v[222:225], v[88:91]
	v_mfma_f32_16x16x32_bf16 v[76:79], v[112:115], v[230:233], v[76:79]
	v_mfma_f32_16x16x32_bf16 v[72:75], v[128:131], v[230:233], v[72:75]
	v_mfma_f32_16x16x32_bf16 v[136:139], v[116:119], v[210:213], v[136:139]
	v_mfma_f32_16x16x32_bf16 v[132:135], v[140:143], v[210:213], v[132:135]
	v_mfma_f32_16x16x32_bf16 v[108:111], v[116:119], v[218:221], v[108:111]
	v_mfma_f32_16x16x32_bf16 v[104:107], v[140:143], v[218:221], v[104:107]
	v_mfma_f32_16x16x32_bf16 v[92:95], v[116:119], v[226:229], v[92:95]
	v_mfma_f32_16x16x32_bf16 v[88:91], v[140:143], v[226:229], v[88:91]
	v_mfma_f32_16x16x32_bf16 v[76:79], v[116:119], v[244:247], v[76:79]
	v_mfma_f32_16x16x32_bf16 v[72:75], v[140:143], v[244:247], v[72:75]
	v_mfma_f32_16x16x32_bf16 v[124:127], v[144:147], v[198:201], v[124:127]
	v_mfma_f32_16x16x32_bf16 v[120:123], v[172:175], v[198:201], v[120:123]
	v_mfma_f32_16x16x32_bf16 v[100:103], v[144:147], v[214:217], v[100:103]
	v_mfma_f32_16x16x32_bf16 v[96:99], v[172:175], v[214:217], v[96:99]
	v_mfma_f32_16x16x32_bf16 v[84:87], v[144:147], v[222:225], v[84:87]
	v_mfma_f32_16x16x32_bf16 v[80:83], v[172:175], v[222:225], v[80:83]
	v_mfma_f32_16x16x32_bf16 v[68:71], v[144:147], v[230:233], v[68:71]
	v_mfma_f32_16x16x32_bf16 v[64:67], v[172:175], v[230:233], v[64:67]
	v_mfma_f32_16x16x32_bf16 v[124:127], v[148:151], v[210:213], v[124:127]
	v_mfma_f32_16x16x32_bf16 v[120:123], v[176:179], v[210:213], v[120:123]
	v_mfma_f32_16x16x32_bf16 v[100:103], v[148:151], v[218:221], v[100:103]
	v_mfma_f32_16x16x32_bf16 v[96:99], v[176:179], v[218:221], v[96:99]
	v_mfma_f32_16x16x32_bf16 v[84:87], v[148:151], v[226:229], v[84:87]
	v_mfma_f32_16x16x32_bf16 v[80:83], v[176:179], v[226:229], v[80:83]
	v_mfma_f32_16x16x32_bf16 v[68:71], v[148:151], v[244:247], v[68:71]
	v_mfma_f32_16x16x32_bf16 v[64:67], v[176:179], v[244:247], v[64:67]
	s_setprio 0
	s_barrier
	s_mov_b32 m0, s44
	v_lshl_add_u64 v[182:183], s[28:29], 0, v[160:161]
	s_add_u32 s68, s28, 0x80000
	ds_read_b128 v[198:201], v185 offset:16384
	ds_read_b128 v[210:213], v185 offset:17408
	ds_read_b128 v[214:217], v185 offset:18432
	ds_read_b128 v[218:221], v185 offset:19456
	ds_read_b128 v[222:225], v185 offset:20480
	ds_read_b128 v[226:229], v185 offset:21504
	ds_read_b128 v[230:233], v185 offset:22528
	ds_read_b128 v[244:247], v185 offset:23552
	global_load_lds_dwordx4 v[182:183], off
	v_lshl_add_u64 v[186:187], s[28:29], 0, v[156:157]
	s_mov_b32 m0, s45
	s_addc_u32 s69, s29, 0
	global_load_lds_dwordx4 v[186:187], off
	v_lshl_add_u64 v[202:203], s[68:69], 0, v[160:161]
	s_mov_b32 m0, s46
	v_lshl_add_u64 v[204:205], s[30:31], 0, v[154:155]
	global_load_lds_dwordx4 v[202:203], off
	v_lshl_add_u64 v[202:203], s[68:69], 0, v[156:157]
	s_mov_b32 m0, s47
	s_nop 0
	global_load_lds_dwordx4 v[202:203], off
	v_lshl_add_u64 v[202:203], s[30:31], 0, v[152:153]
	s_mov_b32 m0, s43
	s_nop 0
	global_load_lds_dwordx4 v[202:203], off
	s_mov_b32 m0, s54
	s_nop 0
	global_load_lds_dwordx4 v[204:205], off
	s_waitcnt vmcnt(8)
	s_waitcnt lgkmcnt(0)
	s_barrier
	s_setprio 1
	s_waitcnt lgkmcnt(0)
	v_mfma_f32_16x16x32_bf16 v[60:63], v[112:115], v[198:201], v[60:63]
	v_mfma_f32_16x16x32_bf16 v[56:59], v[128:131], v[198:201], v[56:59]
	v_mfma_f32_16x16x32_bf16 v[44:47], v[112:115], v[214:217], v[44:47]
	v_mfma_f32_16x16x32_bf16 v[40:43], v[128:131], v[214:217], v[40:43]
	v_mfma_f32_16x16x32_bf16 v[28:31], v[112:115], v[222:225], v[28:31]
	v_mfma_f32_16x16x32_bf16 v[24:27], v[128:131], v[222:225], v[24:27]
	v_mfma_f32_16x16x32_bf16 v[12:15], v[112:115], v[230:233], v[12:15]
	v_mfma_f32_16x16x32_bf16 v[8:11], v[128:131], v[230:233], v[8:11]
	v_mfma_f32_16x16x32_bf16 v[60:63], v[116:119], v[210:213], v[60:63]
	v_mfma_f32_16x16x32_bf16 v[56:59], v[140:143], v[210:213], v[56:59]
	v_mfma_f32_16x16x32_bf16 v[44:47], v[116:119], v[218:221], v[44:47]
	v_mfma_f32_16x16x32_bf16 v[40:43], v[140:143], v[218:221], v[40:43]
	v_mfma_f32_16x16x32_bf16 v[28:31], v[116:119], v[226:229], v[28:31]
	v_mfma_f32_16x16x32_bf16 v[24:27], v[140:143], v[226:229], v[24:27]
	v_mfma_f32_16x16x32_bf16 v[12:15], v[116:119], v[244:247], v[12:15]
	v_mfma_f32_16x16x32_bf16 v[8:11], v[140:143], v[244:247], v[8:11]
	v_mfma_f32_16x16x32_bf16 v[52:55], v[144:147], v[198:201], v[52:55]
	v_mfma_f32_16x16x32_bf16 v[48:51], v[172:175], v[198:201], v[48:51]
	v_mfma_f32_16x16x32_bf16 v[36:39], v[144:147], v[214:217], v[36:39]
	v_mfma_f32_16x16x32_bf16 v[32:35], v[172:175], v[214:217], v[32:35]
	v_mfma_f32_16x16x32_bf16 v[20:23], v[144:147], v[222:225], v[20:23]
	v_mfma_f32_16x16x32_bf16 v[16:19], v[172:175], v[222:225], v[16:19]
	v_mfma_f32_16x16x32_bf16 v[4:7], v[144:147], v[230:233], v[4:7]
	v_mfma_f32_16x16x32_bf16 v[0:3], v[172:175], v[230:233], v[0:3]
	v_mfma_f32_16x16x32_bf16 v[52:55], v[148:151], v[210:213], v[52:55]
	v_mfma_f32_16x16x32_bf16 v[48:51], v[176:179], v[210:213], v[48:51]
	v_mfma_f32_16x16x32_bf16 v[36:39], v[148:151], v[218:221], v[36:39]
	v_mfma_f32_16x16x32_bf16 v[32:35], v[176:179], v[218:221], v[32:35]
	v_mfma_f32_16x16x32_bf16 v[20:23], v[148:151], v[226:229], v[20:23]
	v_mfma_f32_16x16x32_bf16 v[16:19], v[176:179], v[226:229], v[16:19]
	v_mfma_f32_16x16x32_bf16 v[4:7], v[148:151], v[244:247], v[4:7]
	v_mfma_f32_16x16x32_bf16 v[0:3], v[176:179], v[244:247], v[0:3]
	s_setprio 0
	s_barrier
	v_or_b32_e32 v112, 0x18000, v189
	v_add_u32_e32 v116, 0x18400, v189
	v_add_u32_e32 v128, 0x18800, v189
	v_add_u32_e32 v140, 0x18c00, v189
	v_or_b32_e32 v144, 0x1c000, v189
	v_add_u32_e32 v148, 0x1c400, v189
	v_add_u32_e32 v172, 0x1c800, v189
	v_add_u32_e32 v176, 0x1cc00, v189
	ds_read_b128 v[112:115], v112
	ds_read_b128 v[116:119], v116
	ds_read_b128 v[128:131], v128
	ds_read_b128 v[140:143], v140
	ds_read_b128 v[144:147], v144
	ds_read_b128 v[148:151], v148
	ds_read_b128 v[172:175], v172
	ds_read_b128 v[176:179], v176
	s_add_u32 s30, s30, 0x80000
	s_addc_u32 s31, s31, 0
	s_mov_b32 m0, s55
	v_lshl_add_u64 v[234:235], s[30:31], 0, v[152:153]
	ds_read_b128 v[198:201], v185 offset:32768
	ds_read_b128 v[210:213], v185 offset:33792
	ds_read_b128 v[214:217], v185 offset:34816
	ds_read_b128 v[218:221], v185 offset:35840
	ds_read_b128 v[222:225], v185 offset:36864
	ds_read_b128 v[226:229], v185 offset:37888
	ds_read_b128 v[230:233], v185 offset:38912
	ds_read_b128 v[244:247], v185 offset:39936
	global_load_lds_dwordx4 v[234:235], off
	v_lshl_add_u64 v[234:235], s[30:31], 0, v[154:155]
	s_mov_b32 m0, s56
	s_nop 0
	global_load_lds_dwordx4 v[234:235], off
	s_waitcnt vmcnt(8)
	s_waitcnt lgkmcnt(0)
	s_barrier
	s_setprio 1
	s_waitcnt lgkmcnt(0)
	v_mfma_f32_16x16x32_bf16 v[136:139], v[112:115], v[198:201], v[136:139]
	v_mfma_f32_16x16x32_bf16 v[132:135], v[128:131], v[198:201], v[132:135]
	v_mfma_f32_16x16x32_bf16 v[108:111], v[112:115], v[214:217], v[108:111]
	v_mfma_f32_16x16x32_bf16 v[104:107], v[128:131], v[214:217], v[104:107]
	v_mfma_f32_16x16x32_bf16 v[92:95], v[112:115], v[222:225], v[92:95]
	v_mfma_f32_16x16x32_bf16 v[88:91], v[128:131], v[222:225], v[88:91]
	v_mfma_f32_16x16x32_bf16 v[76:79], v[112:115], v[230:233], v[76:79]
	v_mfma_f32_16x16x32_bf16 v[72:75], v[128:131], v[230:233], v[72:75]
	v_mfma_f32_16x16x32_bf16 v[136:139], v[116:119], v[210:213], v[136:139]
	v_mfma_f32_16x16x32_bf16 v[132:135], v[140:143], v[210:213], v[132:135]
	v_mfma_f32_16x16x32_bf16 v[108:111], v[116:119], v[218:221], v[108:111]
	v_mfma_f32_16x16x32_bf16 v[104:107], v[140:143], v[218:221], v[104:107]
	v_mfma_f32_16x16x32_bf16 v[92:95], v[116:119], v[226:229], v[92:95]
	v_mfma_f32_16x16x32_bf16 v[88:91], v[140:143], v[226:229], v[88:91]
	v_mfma_f32_16x16x32_bf16 v[76:79], v[116:119], v[244:247], v[76:79]
	v_mfma_f32_16x16x32_bf16 v[72:75], v[140:143], v[244:247], v[72:75]
	v_mfma_f32_16x16x32_bf16 v[124:127], v[144:147], v[198:201], v[124:127]
	v_mfma_f32_16x16x32_bf16 v[120:123], v[172:175], v[198:201], v[120:123]
	v_mfma_f32_16x16x32_bf16 v[100:103], v[144:147], v[214:217], v[100:103]
	v_mfma_f32_16x16x32_bf16 v[96:99], v[172:175], v[214:217], v[96:99]
	v_mfma_f32_16x16x32_bf16 v[84:87], v[144:147], v[222:225], v[84:87]
	v_mfma_f32_16x16x32_bf16 v[80:83], v[172:175], v[222:225], v[80:83]
	v_mfma_f32_16x16x32_bf16 v[68:71], v[144:147], v[230:233], v[68:71]
	v_mfma_f32_16x16x32_bf16 v[64:67], v[172:175], v[230:233], v[64:67]
	v_mfma_f32_16x16x32_bf16 v[124:127], v[148:151], v[210:213], v[124:127]
	v_mfma_f32_16x16x32_bf16 v[120:123], v[176:179], v[210:213], v[120:123]
	v_mfma_f32_16x16x32_bf16 v[100:103], v[148:151], v[218:221], v[100:103]
	v_mfma_f32_16x16x32_bf16 v[96:99], v[176:179], v[218:221], v[96:99]
	v_mfma_f32_16x16x32_bf16 v[84:87], v[148:151], v[226:229], v[84:87]
	v_mfma_f32_16x16x32_bf16 v[80:83], v[176:179], v[226:229], v[80:83]
	v_mfma_f32_16x16x32_bf16 v[68:71], v[148:151], v[244:247], v[68:71]
	v_mfma_f32_16x16x32_bf16 v[64:67], v[176:179], v[244:247], v[64:67]
	s_setprio 0
	s_barrier
	s_mov_b32 m0, s58
	v_lshl_add_u64 v[182:183], v[182:183], 0, s[40:41]
	s_add_u32 s28, s28, 0x80080
	ds_read_b128 v[198:201], v185 offset:49152
	ds_read_b128 v[210:213], v185 offset:50176
	ds_read_b128 v[214:217], v185 offset:51200
	ds_read_b128 v[218:221], v185 offset:52224
	ds_read_b128 v[222:225], v185 offset:53248
	ds_read_b128 v[226:229], v185 offset:54272
	ds_read_b128 v[230:233], v185 offset:55296
	ds_read_b128 v[244:247], v185 offset:56320
	global_load_lds_dwordx4 v[182:183], off
	v_lshl_add_u64 v[182:183], v[186:187], 0, s[40:41]
	s_mov_b32 m0, s59
	s_addc_u32 s29, s29, 0
	global_load_lds_dwordx4 v[182:183], off
	v_lshl_add_u64 v[182:183], s[28:29], 0, v[160:161]
	s_mov_b32 m0, s62
	s_nop 0
	global_load_lds_dwordx4 v[182:183], off
	v_lshl_add_u64 v[182:183], s[28:29], 0, v[156:157]
	s_mov_b32 m0, s63
	s_nop 0
	global_load_lds_dwordx4 v[182:183], off
	v_lshl_add_u64 v[182:183], v[202:203], 0, s[40:41]
	s_mov_b32 m0, s60
	s_nop 0
	global_load_lds_dwordx4 v[182:183], off
	v_lshl_add_u64 v[182:183], v[204:205], 0, s[40:41]
	s_mov_b32 m0, s61
	s_nop 0
	global_load_lds_dwordx4 v[182:183], off
	s_waitcnt vmcnt(8)
	s_waitcnt lgkmcnt(0)
	s_barrier
	s_setprio 1
	s_waitcnt lgkmcnt(0)
	v_mfma_f32_16x16x32_bf16 v[60:63], v[112:115], v[198:201], v[60:63]
	v_mfma_f32_16x16x32_bf16 v[56:59], v[128:131], v[198:201], v[56:59]
	v_mfma_f32_16x16x32_bf16 v[44:47], v[112:115], v[214:217], v[44:47]
	v_mfma_f32_16x16x32_bf16 v[40:43], v[128:131], v[214:217], v[40:43]
	v_mfma_f32_16x16x32_bf16 v[28:31], v[112:115], v[222:225], v[28:31]
	v_mfma_f32_16x16x32_bf16 v[24:27], v[128:131], v[222:225], v[24:27]
	v_mfma_f32_16x16x32_bf16 v[12:15], v[112:115], v[230:233], v[12:15]
	v_mfma_f32_16x16x32_bf16 v[8:11], v[128:131], v[230:233], v[8:11]
	v_mfma_f32_16x16x32_bf16 v[60:63], v[116:119], v[210:213], v[60:63]
	v_mfma_f32_16x16x32_bf16 v[56:59], v[140:143], v[210:213], v[56:59]
	v_mfma_f32_16x16x32_bf16 v[44:47], v[116:119], v[218:221], v[44:47]
	v_mfma_f32_16x16x32_bf16 v[40:43], v[140:143], v[218:221], v[40:43]
	v_mfma_f32_16x16x32_bf16 v[28:31], v[116:119], v[226:229], v[28:31]
	v_mfma_f32_16x16x32_bf16 v[24:27], v[140:143], v[226:229], v[24:27]
	v_mfma_f32_16x16x32_bf16 v[12:15], v[116:119], v[244:247], v[12:15]
	v_mfma_f32_16x16x32_bf16 v[8:11], v[140:143], v[244:247], v[8:11]
	v_mfma_f32_16x16x32_bf16 v[52:55], v[144:147], v[198:201], v[52:55]
	v_mfma_f32_16x16x32_bf16 v[48:51], v[172:175], v[198:201], v[48:51]
	v_mfma_f32_16x16x32_bf16 v[36:39], v[144:147], v[214:217], v[36:39]
	v_mfma_f32_16x16x32_bf16 v[32:35], v[172:175], v[214:217], v[32:35]
	v_mfma_f32_16x16x32_bf16 v[20:23], v[144:147], v[222:225], v[20:23]
	v_mfma_f32_16x16x32_bf16 v[16:19], v[172:175], v[222:225], v[16:19]
	v_mfma_f32_16x16x32_bf16 v[4:7], v[144:147], v[230:233], v[4:7]
	v_mfma_f32_16x16x32_bf16 v[0:3], v[172:175], v[230:233], v[0:3]
	v_mfma_f32_16x16x32_bf16 v[52:55], v[148:151], v[210:213], v[52:55]
	v_mfma_f32_16x16x32_bf16 v[48:51], v[176:179], v[210:213], v[48:51]
	v_mfma_f32_16x16x32_bf16 v[36:39], v[148:151], v[218:221], v[36:39]
	v_mfma_f32_16x16x32_bf16 v[32:35], v[176:179], v[218:221], v[32:35]
	v_mfma_f32_16x16x32_bf16 v[20:23], v[148:151], v[226:229], v[20:23]
	v_mfma_f32_16x16x32_bf16 v[16:19], v[176:179], v[226:229], v[16:19]
	v_mfma_f32_16x16x32_bf16 v[4:7], v[148:151], v[244:247], v[4:7]
	v_mfma_f32_16x16x32_bf16 v[0:3], v[176:179], v[244:247], v[0:3]
	s_setprio 0
	s_barrier
	s_add_i32 s67, s67, 2
	s_add_u32 s38, s38, 0x100
	s_addc_u32 s66, s66, 0
	s_add_u32 s26, s26, 0x100
	s_addc_u32 s27, s27, 0
	s_cmp_gt_u32 s67, 29
	s_cbranch_scc0 .LBB0_1081
	s_and_b64 vcc, exec, s[12:13]
	s_cbranch_vccz .LBB0_1084
	s_barrier
